# DIFF item epilogue: gate loads prefetched and sub-norm gain loads software-pipelined one group ahead
# speedup vs baseline: 1.0045x; 1.0045x over previous
; template <bool DIFF>
; DI void attn_phase(const AttnArgs& a, char* lds) {
;     ...
;       if (comp == 1) {
;         const float f = inv * lam;
; #pragma unroll
;         for (int m = 0; m < NM; ++m)
; #pragma unroll
;           for (int r = 0; r < 16; ++r) { ex[(m * 16 + r) * 64] = o[m][r] * f; if (r == 15) __builtin_amdgcn_sched_barrier(0); }
;       }
;       __syncthreads();
;       if (comp == 0) {
;         float ss = 0.f;
; #pragma unroll
;         for (int m = 0; m < NM; ++m)
; #pragma unroll
;           for (int r = 0; r < 16; ++r) { const float d = o[m][r] * inv - ex[(m * 16 + r) * 64]; o[m][r] = d; ss += d * d; if (r == 15) asm volatile("" : "+v"(ss) :: "memory"); }
.LBB0_633:
	s_andn2_b64 vcc, exec, s[14:15]
	s_waitcnt lgkmcnt(0)
	s_barrier
	s_cbranch_vccnz .LBB0_587
	v_lshrrev_b32_e32 v152, 5, v4
	ds_read2st64_b32 v[4:5], v2 offset1:1
	ds_read2st64_b32 v[6:7], v2 offset0:2 offset1:3
	ds_read2st64_b32 v[8:9], v2 offset0:4 offset1:5
	ds_read2st64_b32 v[10:11], v2 offset0:6 offset1:7
	ds_read2st64_b32 v[12:13], v2 offset0:8 offset1:9
	ds_read2st64_b32 v[154:155], v2 offset0:10 offset1:11
	ds_read2st64_b32 v[156:157], v2 offset0:12 offset1:13
	ds_read2st64_b32 v[158:159], v2 offset0:14 offset1:15
	s_waitcnt lgkmcnt(7)
	v_pk_fma_f32 v[150:151], v[128:129], v[0:1], v[4:5] op_sel_hi:[1,0,1] neg_lo:[0,0,1] neg_hi:[0,0,1]
	v_and_or_b32 v3, v3, 31, s76
	v_lshl_or_b32 v14, v152, 3, s75
	s_waitcnt lgkmcnt(6)
	v_pk_fma_f32 v[148:149], v[130:131], v[0:1], v[6:7] op_sel_hi:[1,0,1] neg_lo:[0,0,1] neg_hi:[0,0,1]
	v_pk_mul_f32 v[4:5], v[150:151], v[150:151]
	v_lshl_add_u32 v14, v3, 11, v14
	v_pk_mul_f32 v[6:7], v[148:149], v[148:149]
	v_add_f32_e32 v3, v4, v5
	s_waitcnt lgkmcnt(5)
	v_pk_fma_f32 v[146:147], v[132:133], v[0:1], v[8:9] op_sel_hi:[1,0,1] neg_lo:[0,0,1] neg_hi:[0,0,1]
	v_add_f32_e32 v3, v3, v6
	v_pk_mul_f32 v[8:9], v[146:147], v[146:147]
	v_add_f32_e32 v3, v3, v7
	s_waitcnt lgkmcnt(4)
	v_pk_fma_f32 v[144:145], v[134:135], v[0:1], v[10:11] op_sel_hi:[1,0,1] neg_lo:[0,0,1] neg_hi:[0,0,1]
	v_add_f32_e32 v3, v3, v8
	v_pk_mul_f32 v[10:11], v[144:145], v[144:145]
	v_add_f32_e32 v3, v3, v9
	s_waitcnt lgkmcnt(3)
	v_pk_fma_f32 v[136:137], v[136:137], v[0:1], v[12:13] op_sel_hi:[1,0,1] neg_lo:[0,0,1] neg_hi:[0,0,1]
	v_add_f32_e32 v3, v3, v10
	v_pk_mul_f32 v[12:13], v[136:137], v[136:137]
	v_add_f32_e32 v3, v3, v11
	s_waitcnt lgkmcnt(2)
	v_pk_fma_f32 v[138:139], v[138:139], v[0:1], v[154:155] op_sel_hi:[1,0,1] neg_lo:[0,0,1] neg_hi:[0,0,1]
	v_add_f32_e32 v3, v3, v12
	v_pk_mul_f32 v[132:133], v[138:139], v[138:139]
	v_add_f32_e32 v3, v3, v13
	s_waitcnt lgkmcnt(1)
	v_pk_fma_f32 v[140:141], v[140:141], v[0:1], v[156:157] op_sel_hi:[1,0,1] neg_lo:[0,0,1] neg_hi:[0,0,1]
	v_add_f32_e32 v3, v3, v132
	v_pk_mul_f32 v[130:131], v[140:141], v[140:141]
	v_add_f32_e32 v3, v3, v133
	s_waitcnt lgkmcnt(0)
	v_pk_fma_f32 v[142:143], v[142:143], v[0:1], v[158:159] op_sel_hi:[1,0,1] neg_lo:[0,0,1] neg_hi:[0,0,1]
	v_add_f32_e32 v3, v3, v130
	v_pk_mul_f32 v[128:129], v[142:143], v[142:143]
	v_add_f32_e32 v3, v3, v131
	v_add_f32_e32 v3, v3, v128
	v_add_f32_e32 v3, v3, v129
	ds_read2st64_b32 v[4:5], v2 offset0:16 offset1:17
	ds_read2st64_b32 v[6:7], v2 offset0:18 offset1:19
	ds_read2st64_b32 v[8:9], v2 offset0:20 offset1:21
	ds_read2st64_b32 v[10:11], v2 offset0:22 offset1:23
	ds_read2st64_b32 v[12:13], v2 offset0:24 offset1:25
	ds_read2st64_b32 v[154:155], v2 offset0:26 offset1:27
	ds_read2st64_b32 v[156:157], v2 offset0:28 offset1:29
	ds_read2st64_b32 v[158:159], v2 offset0:30 offset1:31
	s_waitcnt lgkmcnt(7)
	v_pk_fma_f32 v[134:135], v[112:113], v[0:1], v[4:5] op_sel_hi:[1,0,1] neg_lo:[0,0,1] neg_hi:[0,0,1]
	s_waitcnt lgkmcnt(6)
	v_pk_fma_f32 v[132:133], v[114:115], v[0:1], v[6:7] op_sel_hi:[1,0,1] neg_lo:[0,0,1] neg_hi:[0,0,1]
	v_pk_mul_f32 v[4:5], v[134:135], v[134:135]
	v_pk_mul_f32 v[6:7], v[132:133], v[132:133]
	v_add_f32_e32 v3, v3, v4
	v_add_f32_e32 v3, v3, v5
	s_waitcnt lgkmcnt(5)
	v_pk_fma_f32 v[130:131], v[116:117], v[0:1], v[8:9] op_sel_hi:[1,0,1] neg_lo:[0,0,1] neg_hi:[0,0,1]
	v_add_f32_e32 v3, v3, v6
	v_pk_mul_f32 v[8:9], v[130:131], v[130:131]
	v_add_f32_e32 v3, v3, v7
	s_waitcnt lgkmcnt(4)
	v_pk_fma_f32 v[128:129], v[118:119], v[0:1], v[10:11] op_sel_hi:[1,0,1] neg_lo:[0,0,1] neg_hi:[0,0,1]
	v_add_f32_e32 v3, v3, v8
	v_pk_mul_f32 v[10:11], v[128:129], v[128:129]
	v_add_f32_e32 v3, v3, v9
	v_add_f32_e32 v3, v3, v10
	s_waitcnt lgkmcnt(3)
	v_pk_fma_f32 v[120:121], v[120:121], v[0:1], v[12:13] op_sel_hi:[1,0,1] neg_lo:[0,0,1] neg_hi:[0,0,1]
	v_add_f32_e32 v3, v3, v11
	v_pk_mul_f32 v[10:11], v[120:121], v[120:121]
	s_waitcnt lgkmcnt(2)
	v_pk_fma_f32 v[122:123], v[122:123], v[0:1], v[154:155] op_sel_hi:[1,0,1] neg_lo:[0,0,1] neg_hi:[0,0,1]
	v_add_f32_e32 v3, v3, v10
	v_pk_mul_f32 v[8:9], v[122:123], v[122:123]
	v_add_f32_e32 v3, v3, v11
	s_waitcnt lgkmcnt(1)
	v_pk_fma_f32 v[124:125], v[124:125], v[0:1], v[156:157] op_sel_hi:[1,0,1] neg_lo:[0,0,1] neg_hi:[0,0,1]
	v_add_f32_e32 v3, v3, v8
	v_pk_mul_f32 v[6:7], v[124:125], v[124:125]
	v_add_f32_e32 v3, v3, v9
	s_waitcnt lgkmcnt(0)
	v_pk_fma_f32 v[126:127], v[126:127], v[0:1], v[158:159] op_sel_hi:[1,0,1] neg_lo:[0,0,1] neg_hi:[0,0,1]
	v_add_f32_e32 v3, v3, v6
	v_pk_mul_f32 v[4:5], v[126:127], v[126:127]
	v_add_f32_e32 v3, v3, v7
	v_add_f32_e32 v3, v3, v4
	v_add_f32_e32 v3, v3, v5
	ds_read2st64_b32 v[4:5], v2 offset0:32 offset1:33
	ds_read2st64_b32 v[6:7], v2 offset0:34 offset1:35
	ds_read2st64_b32 v[8:9], v2 offset0:36 offset1:37
	ds_read2st64_b32 v[10:11], v2 offset0:38 offset1:39
	ds_read2st64_b32 v[12:13], v2 offset0:40 offset1:41
	ds_read2st64_b32 v[154:155], v2 offset0:42 offset1:43
	ds_read2st64_b32 v[156:157], v2 offset0:44 offset1:45
	ds_read2st64_b32 v[158:159], v2 offset0:46 offset1:47
	s_waitcnt lgkmcnt(7)
	v_pk_fma_f32 v[118:119], v[96:97], v[0:1], v[4:5] op_sel_hi:[1,0,1] neg_lo:[0,0,1] neg_hi:[0,0,1]
	s_waitcnt lgkmcnt(6)
	v_pk_fma_f32 v[116:117], v[98:99], v[0:1], v[6:7] op_sel_hi:[1,0,1] neg_lo:[0,0,1] neg_hi:[0,0,1]
	v_pk_mul_f32 v[4:5], v[118:119], v[118:119]
	v_pk_mul_f32 v[6:7], v[116:117], v[116:117]
	v_add_f32_e32 v3, v3, v4
	v_add_f32_e32 v3, v3, v5
	s_waitcnt lgkmcnt(5)
	v_pk_fma_f32 v[114:115], v[100:101], v[0:1], v[8:9] op_sel_hi:[1,0,1] neg_lo:[0,0,1] neg_hi:[0,0,1]
	v_add_f32_e32 v3, v3, v6
	v_pk_mul_f32 v[8:9], v[114:115], v[114:115]
	v_add_f32_e32 v3, v3, v7
	s_waitcnt lgkmcnt(4)
; template <bool DIFF>
; DI void attn_phase(const AttnArgs& a, char* lds) {
;     ...
;         float ss = 0.f;
; #pragma unroll
;         for (int m = 0; m < NM; ++m)
; #pragma unroll
;           for (int r = 0; r < 16; ++r) { const float d = o[m][r] * inv - ex[(m * 16 + r) * 64]; o[m][r] = d; ss += d * d; if (r == 15) asm volatile("" : "+v"(ss) :: "memory"); }
	v_pk_fma_f32 v[112:113], v[102:103], v[0:1], v[10:11] op_sel_hi:[1,0,1] neg_lo:[0,0,1] neg_hi:[0,0,1]
	v_add_f32_e32 v3, v3, v8
	v_pk_mul_f32 v[10:11], v[112:113], v[112:113]
	v_add_f32_e32 v3, v3, v9
	v_add_f32_e32 v3, v3, v10
	s_waitcnt lgkmcnt(3)
	v_pk_fma_f32 v[104:105], v[104:105], v[0:1], v[12:13] op_sel_hi:[1,0,1] neg_lo:[0,0,1] neg_hi:[0,0,1]
	v_add_f32_e32 v3, v3, v11
	v_pk_mul_f32 v[10:11], v[104:105], v[104:105]
	s_waitcnt lgkmcnt(2)
	v_pk_fma_f32 v[106:107], v[106:107], v[0:1], v[154:155] op_sel_hi:[1,0,1] neg_lo:[0,0,1] neg_hi:[0,0,1]
	v_add_f32_e32 v3, v3, v10
	v_pk_mul_f32 v[8:9], v[106:107], v[106:107]
	v_add_f32_e32 v3, v3, v11
	s_waitcnt lgkmcnt(1)
	v_pk_fma_f32 v[108:109], v[108:109], v[0:1], v[156:157] op_sel_hi:[1,0,1] neg_lo:[0,0,1] neg_hi:[0,0,1]
	v_add_f32_e32 v3, v3, v8
	v_pk_mul_f32 v[6:7], v[108:109], v[108:109]
	v_add_f32_e32 v3, v3, v9
	s_waitcnt lgkmcnt(0)
	v_pk_fma_f32 v[110:111], v[110:111], v[0:1], v[158:159] op_sel_hi:[1,0,1] neg_lo:[0,0,1] neg_hi:[0,0,1]
	v_add_f32_e32 v3, v3, v6
	v_pk_mul_f32 v[4:5], v[110:111], v[110:111]
	v_add_f32_e32 v3, v3, v7
	v_add_f32_e32 v3, v3, v4
	v_add_f32_e32 v3, v3, v5
	ds_read2st64_b32 v[4:5], v2 offset0:48 offset1:49
	ds_read2st64_b32 v[6:7], v2 offset0:50 offset1:51
	ds_read2st64_b32 v[8:9], v2 offset0:52 offset1:53
	ds_read2st64_b32 v[10:11], v2 offset0:54 offset1:55
	ds_read2st64_b32 v[12:13], v2 offset0:56 offset1:57
	ds_read2st64_b32 v[154:155], v2 offset0:58 offset1:59
	ds_read2st64_b32 v[156:157], v2 offset0:60 offset1:61
	ds_read2st64_b32 v[158:159], v2 offset0:62 offset1:63
	s_waitcnt lgkmcnt(7)
	v_pk_fma_f32 v[102:103], v[80:81], v[0:1], v[4:5] op_sel_hi:[1,0,1] neg_lo:[0,0,1] neg_hi:[0,0,1]
	s_waitcnt lgkmcnt(6)
	v_pk_fma_f32 v[100:101], v[82:83], v[0:1], v[6:7] op_sel_hi:[1,0,1] neg_lo:[0,0,1] neg_hi:[0,0,1]
	v_pk_mul_f32 v[4:5], v[102:103], v[102:103]
	v_pk_mul_f32 v[6:7], v[100:101], v[100:101]
	v_add_f32_e32 v3, v3, v4
	v_add_f32_e32 v3, v3, v5
	s_waitcnt lgkmcnt(5)
	v_pk_fma_f32 v[98:99], v[84:85], v[0:1], v[8:9] op_sel_hi:[1,0,1] neg_lo:[0,0,1] neg_hi:[0,0,1]
	v_add_f32_e32 v3, v3, v6
	v_pk_mul_f32 v[8:9], v[98:99], v[98:99]
	v_add_f32_e32 v3, v3, v7
	s_waitcnt lgkmcnt(4)
	v_pk_fma_f32 v[96:97], v[86:87], v[0:1], v[10:11] op_sel_hi:[1,0,1] neg_lo:[0,0,1] neg_hi:[0,0,1]
	v_add_f32_e32 v3, v3, v8
	v_pk_mul_f32 v[10:11], v[96:97], v[96:97]
	v_add_f32_e32 v3, v3, v9
	v_add_f32_e32 v3, v3, v10
	s_waitcnt lgkmcnt(3)
	v_pk_fma_f32 v[88:89], v[88:89], v[0:1], v[12:13] op_sel_hi:[1,0,1] neg_lo:[0,0,1] neg_hi:[0,0,1]
	v_add_f32_e32 v3, v3, v11
	v_pk_mul_f32 v[10:11], v[88:89], v[88:89]
	s_waitcnt lgkmcnt(2)
	v_pk_fma_f32 v[90:91], v[90:91], v[0:1], v[154:155] op_sel_hi:[1,0,1] neg_lo:[0,0,1] neg_hi:[0,0,1]
	v_add_f32_e32 v3, v3, v10
	v_pk_mul_f32 v[8:9], v[90:91], v[90:91]
	v_add_f32_e32 v3, v3, v11
	s_waitcnt lgkmcnt(1)
	v_pk_fma_f32 v[92:93], v[92:93], v[0:1], v[156:157] op_sel_hi:[1,0,1] neg_lo:[0,0,1] neg_hi:[0,0,1]
	v_add_f32_e32 v3, v3, v8
	v_pk_mul_f32 v[6:7], v[92:93], v[92:93]
	v_add_f32_e32 v3, v3, v9
	s_waitcnt lgkmcnt(0)
	v_pk_fma_f32 v[94:95], v[94:95], v[0:1], v[158:159] op_sel_hi:[1,0,1] neg_lo:[0,0,1] neg_hi:[0,0,1]
	v_add_f32_e32 v3, v3, v6
	v_pk_mul_f32 v[4:5], v[94:95], v[94:95]
	v_add_f32_e32 v3, v3, v7
	v_add_f32_e32 v3, v3, v4
	v_add_f32_e32 v3, v3, v5
	ds_read2st64_b32 v[4:5], v2 offset0:64 offset1:65
	ds_read2st64_b32 v[6:7], v2 offset0:66 offset1:67
	ds_read2st64_b32 v[8:9], v2 offset0:68 offset1:69
	ds_read2st64_b32 v[10:11], v2 offset0:70 offset1:71
	ds_read2st64_b32 v[12:13], v2 offset0:72 offset1:73
	ds_read2st64_b32 v[154:155], v2 offset0:74 offset1:75
	ds_read2st64_b32 v[156:157], v2 offset0:76 offset1:77
	ds_read2st64_b32 v[158:159], v2 offset0:78 offset1:79
	s_waitcnt lgkmcnt(7)
	v_pk_fma_f32 v[86:87], v[64:65], v[0:1], v[4:5] op_sel_hi:[1,0,1] neg_lo:[0,0,1] neg_hi:[0,0,1]
	s_waitcnt lgkmcnt(6)
	v_pk_fma_f32 v[84:85], v[66:67], v[0:1], v[6:7] op_sel_hi:[1,0,1] neg_lo:[0,0,1] neg_hi:[0,0,1]
	v_pk_mul_f32 v[4:5], v[86:87], v[86:87]
	v_pk_mul_f32 v[6:7], v[84:85], v[84:85]
	v_add_f32_e32 v3, v3, v4
	v_add_f32_e32 v3, v3, v5
	s_waitcnt lgkmcnt(5)
	v_pk_fma_f32 v[82:83], v[68:69], v[0:1], v[8:9] op_sel_hi:[1,0,1] neg_lo:[0,0,1] neg_hi:[0,0,1]
	v_add_f32_e32 v3, v3, v6
	v_pk_mul_f32 v[8:9], v[82:83], v[82:83]
	v_add_f32_e32 v3, v3, v7
	s_waitcnt lgkmcnt(4)
	v_pk_fma_f32 v[80:81], v[70:71], v[0:1], v[10:11] op_sel_hi:[1,0,1] neg_lo:[0,0,1] neg_hi:[0,0,1]
	v_add_f32_e32 v3, v3, v8
	v_pk_mul_f32 v[10:11], v[80:81], v[80:81]
	v_add_f32_e32 v3, v3, v9
	v_add_f32_e32 v3, v3, v10
	s_waitcnt lgkmcnt(3)
	v_pk_fma_f32 v[72:73], v[72:73], v[0:1], v[12:13] op_sel_hi:[1,0,1] neg_lo:[0,0,1] neg_hi:[0,0,1]
	v_add_f32_e32 v3, v3, v11
	v_pk_mul_f32 v[10:11], v[72:73], v[72:73]
	s_waitcnt lgkmcnt(2)
	v_pk_fma_f32 v[74:75], v[74:75], v[0:1], v[154:155] op_sel_hi:[1,0,1] neg_lo:[0,0,1] neg_hi:[0,0,1]
	v_add_f32_e32 v3, v3, v10
	v_pk_mul_f32 v[8:9], v[74:75], v[74:75]
	v_add_f32_e32 v3, v3, v11
	s_waitcnt lgkmcnt(1)
	v_pk_fma_f32 v[76:77], v[76:77], v[0:1], v[156:157] op_sel_hi:[1,0,1] neg_lo:[0,0,1] neg_hi:[0,0,1]
	v_add_f32_e32 v3, v3, v8
	v_pk_mul_f32 v[6:7], v[76:77], v[76:77]
	v_add_f32_e32 v3, v3, v9
	s_waitcnt lgkmcnt(0)
	v_pk_fma_f32 v[78:79], v[78:79], v[0:1], v[158:159] op_sel_hi:[1,0,1] neg_lo:[0,0,1] neg_hi:[0,0,1]
	v_add_f32_e32 v3, v3, v6
	v_pk_mul_f32 v[4:5], v[78:79], v[78:79]
	v_add_f32_e32 v3, v3, v7
	v_add_f32_e32 v3, v3, v4
	v_add_f32_e32 v3, v3, v5
	ds_read2st64_b32 v[4:5], v2 offset0:80 offset1:81
	ds_read2st64_b32 v[6:7], v2 offset0:82 offset1:83
	ds_read2st64_b32 v[8:9], v2 offset0:84 offset1:85
	ds_read2st64_b32 v[10:11], v2 offset0:86 offset1:87
	ds_read2st64_b32 v[12:13], v2 offset0:88 offset1:89
	ds_read2st64_b32 v[154:155], v2 offset0:90 offset1:91
	ds_read2st64_b32 v[156:157], v2 offset0:92 offset1:93
	ds_read2st64_b32 v[158:159], v2 offset0:94 offset1:95
	s_waitcnt lgkmcnt(7)
; template <bool DIFF>
; DI void attn_phase(const AttnArgs& a, char* lds) {
;     ...
;         float ss = 0.f;
; #pragma unroll
;         for (int m = 0; m < NM; ++m)
; #pragma unroll
;           for (int r = 0; r < 16; ++r) { const float d = o[m][r] * inv - ex[(m * 16 + r) * 64]; o[m][r] = d; ss += d * d; if (r == 15) asm volatile("" : "+v"(ss) :: "memory"); }
	v_pk_fma_f32 v[70:71], v[48:49], v[0:1], v[4:5] op_sel_hi:[1,0,1] neg_lo:[0,0,1] neg_hi:[0,0,1]
	s_waitcnt lgkmcnt(6)
	v_pk_fma_f32 v[68:69], v[50:51], v[0:1], v[6:7] op_sel_hi:[1,0,1] neg_lo:[0,0,1] neg_hi:[0,0,1]
	v_pk_mul_f32 v[4:5], v[70:71], v[70:71]
	v_pk_mul_f32 v[6:7], v[68:69], v[68:69]
	v_add_f32_e32 v3, v3, v4
	v_add_f32_e32 v3, v3, v5
	s_waitcnt lgkmcnt(5)
	v_pk_fma_f32 v[66:67], v[52:53], v[0:1], v[8:9] op_sel_hi:[1,0,1] neg_lo:[0,0,1] neg_hi:[0,0,1]
	v_add_f32_e32 v3, v3, v6
	v_pk_mul_f32 v[8:9], v[66:67], v[66:67]
	v_add_f32_e32 v3, v3, v7
	s_waitcnt lgkmcnt(4)
	v_pk_fma_f32 v[64:65], v[54:55], v[0:1], v[10:11] op_sel_hi:[1,0,1] neg_lo:[0,0,1] neg_hi:[0,0,1]
	v_add_f32_e32 v3, v3, v8
	v_pk_mul_f32 v[10:11], v[64:65], v[64:65]
	v_add_f32_e32 v3, v3, v9
	v_add_f32_e32 v3, v3, v10
	s_waitcnt lgkmcnt(3)
	v_pk_fma_f32 v[56:57], v[56:57], v[0:1], v[12:13] op_sel_hi:[1,0,1] neg_lo:[0,0,1] neg_hi:[0,0,1]
	v_add_f32_e32 v3, v3, v11
	v_pk_mul_f32 v[10:11], v[56:57], v[56:57]
	s_waitcnt lgkmcnt(2)
	v_pk_fma_f32 v[58:59], v[58:59], v[0:1], v[154:155] op_sel_hi:[1,0,1] neg_lo:[0,0,1] neg_hi:[0,0,1]
	v_add_f32_e32 v3, v3, v10
	v_pk_mul_f32 v[8:9], v[58:59], v[58:59]
	v_add_f32_e32 v3, v3, v11
	s_waitcnt lgkmcnt(1)
	v_pk_fma_f32 v[60:61], v[60:61], v[0:1], v[156:157] op_sel_hi:[1,0,1] neg_lo:[0,0,1] neg_hi:[0,0,1]
	v_add_f32_e32 v3, v3, v8
	v_pk_mul_f32 v[6:7], v[60:61], v[60:61]
	v_add_f32_e32 v3, v3, v9
	s_waitcnt lgkmcnt(0)
	v_pk_fma_f32 v[62:63], v[62:63], v[0:1], v[158:159] op_sel_hi:[1,0,1] neg_lo:[0,0,1] neg_hi:[0,0,1]
	v_add_f32_e32 v3, v3, v6
	v_pk_mul_f32 v[4:5], v[62:63], v[62:63]
	v_add_f32_e32 v3, v3, v7
	v_add_f32_e32 v3, v3, v4
	v_add_f32_e32 v3, v3, v5
	ds_read2st64_b32 v[4:5], v2 offset0:96 offset1:97
	ds_read2st64_b32 v[6:7], v2 offset0:98 offset1:99
	ds_read2st64_b32 v[8:9], v2 offset0:100 offset1:101
	ds_read2st64_b32 v[10:11], v2 offset0:102 offset1:103
	ds_read2st64_b32 v[12:13], v2 offset0:104 offset1:105
	ds_read2st64_b32 v[154:155], v2 offset0:106 offset1:107
	ds_read2st64_b32 v[156:157], v2 offset0:108 offset1:109
	ds_read2st64_b32 v[158:159], v2 offset0:110 offset1:111
	s_waitcnt lgkmcnt(7)
	v_pk_fma_f32 v[54:55], v[32:33], v[0:1], v[4:5] op_sel_hi:[1,0,1] neg_lo:[0,0,1] neg_hi:[0,0,1]
	s_waitcnt lgkmcnt(6)
	v_pk_fma_f32 v[52:53], v[34:35], v[0:1], v[6:7] op_sel_hi:[1,0,1] neg_lo:[0,0,1] neg_hi:[0,0,1]
	v_pk_mul_f32 v[4:5], v[54:55], v[54:55]
	v_pk_mul_f32 v[6:7], v[52:53], v[52:53]
	v_add_f32_e32 v3, v3, v4
	v_add_f32_e32 v3, v3, v5
	s_waitcnt lgkmcnt(5)
	v_pk_fma_f32 v[50:51], v[36:37], v[0:1], v[8:9] op_sel_hi:[1,0,1] neg_lo:[0,0,1] neg_hi:[0,0,1]
	v_add_f32_e32 v3, v3, v6
	v_pk_mul_f32 v[8:9], v[50:51], v[50:51]
	v_add_f32_e32 v3, v3, v7
	s_waitcnt lgkmcnt(4)
	v_pk_fma_f32 v[48:49], v[38:39], v[0:1], v[10:11] op_sel_hi:[1,0,1] neg_lo:[0,0,1] neg_hi:[0,0,1]
	v_add_f32_e32 v3, v3, v8
	v_pk_mul_f32 v[10:11], v[48:49], v[48:49]
	v_add_f32_e32 v3, v3, v9
	v_add_f32_e32 v3, v3, v10
	s_waitcnt lgkmcnt(3)
	v_pk_fma_f32 v[38:39], v[40:41], v[0:1], v[12:13] op_sel_hi:[1,0,1] neg_lo:[0,0,1] neg_hi:[0,0,1]
	v_add_f32_e32 v3, v3, v11
	v_pk_mul_f32 v[10:11], v[38:39], v[38:39]
	s_waitcnt lgkmcnt(2)
	v_pk_fma_f32 v[36:37], v[42:43], v[0:1], v[154:155] op_sel_hi:[1,0,1] neg_lo:[0,0,1] neg_hi:[0,0,1]
	v_add_f32_e32 v3, v3, v10
	v_pk_mul_f32 v[8:9], v[36:37], v[36:37]
	v_add_f32_e32 v3, v3, v11
	s_waitcnt lgkmcnt(1)
	v_pk_fma_f32 v[34:35], v[44:45], v[0:1], v[156:157] op_sel_hi:[1,0,1] neg_lo:[0,0,1] neg_hi:[0,0,1]
	v_add_f32_e32 v3, v3, v8
	v_pk_mul_f32 v[6:7], v[34:35], v[34:35]
	v_add_f32_e32 v3, v3, v9
	s_waitcnt lgkmcnt(0)
	v_pk_fma_f32 v[32:33], v[46:47], v[0:1], v[158:159] op_sel_hi:[1,0,1] neg_lo:[0,0,1] neg_hi:[0,0,1]
	v_add_f32_e32 v3, v3, v6
	v_pk_mul_f32 v[4:5], v[32:33], v[32:33]
	v_add_f32_e32 v3, v3, v7
	v_add_f32_e32 v3, v3, v4
	v_add_f32_e32 v44, v3, v5
	ds_read2st64_b32 v[4:5], v2 offset0:112 offset1:113
	ds_read2st64_b32 v[6:7], v2 offset0:114 offset1:115
	ds_read2st64_b32 v[8:9], v2 offset0:116 offset1:117
	ds_read2st64_b32 v[10:11], v2 offset0:118 offset1:119
	ds_read2st64_b32 v[12:13], v2 offset0:120 offset1:121
	ds_read2st64_b32 v[40:41], v2 offset0:122 offset1:123
	ds_read2st64_b32 v[42:43], v2 offset0:124 offset1:125
	ds_read2st64_b32 v[2:3], v2 offset0:126 offset1:127
	s_waitcnt lgkmcnt(7)
	v_pk_fma_f32 v[16:17], v[16:17], v[0:1], v[4:5] op_sel_hi:[1,0,1] neg_lo:[0,0,1] neg_hi:[0,0,1]
	s_waitcnt lgkmcnt(6)
	v_pk_fma_f32 v[18:19], v[18:19], v[0:1], v[6:7] op_sel_hi:[1,0,1] neg_lo:[0,0,1] neg_hi:[0,0,1]
	v_pk_mul_f32 v[4:5], v[16:17], v[16:17]
	v_pk_mul_f32 v[6:7], v[18:19], v[18:19]
	v_add_f32_e32 v4, v44, v4
	v_add_f32_e32 v4, v4, v5
	s_waitcnt lgkmcnt(5)
	v_pk_fma_f32 v[20:21], v[20:21], v[0:1], v[8:9] op_sel_hi:[1,0,1] neg_lo:[0,0,1] neg_hi:[0,0,1]
	v_add_f32_e32 v4, v4, v6
	v_pk_mul_f32 v[8:9], v[20:21], v[20:21]
	v_add_f32_e32 v4, v4, v7
	s_waitcnt lgkmcnt(4)
	v_pk_fma_f32 v[10:11], v[22:23], v[0:1], v[10:11] op_sel_hi:[1,0,1] neg_lo:[0,0,1] neg_hi:[0,0,1]
	v_add_f32_e32 v4, v4, v8
	v_pk_mul_f32 v[22:23], v[10:11], v[10:11]
	v_add_f32_e32 v4, v4, v9
	v_add_f32_e32 v4, v4, v22
	s_waitcnt lgkmcnt(3)
	v_pk_fma_f32 v[8:9], v[24:25], v[0:1], v[12:13] op_sel_hi:[1,0,1] neg_lo:[0,0,1] neg_hi:[0,0,1]
	v_add_f32_e32 v44, v4, v23
	v_pk_mul_f32 v[12:13], v[8:9], v[8:9]
	s_waitcnt lgkmcnt(0)
; DI float bflo(u32 u) { return __uint_as_float(u << 16); }
; template <bool DIFF>
; DI void attn_phase(const AttnArgs& a, char* lds) {
;     ...
;           for (int r = 0; r < 16; ++r) { const float d = o[m][r] * inv - ex[(m * 16 + r) * 64]; o[m][r] = d; ss += d * d; if (r == 15) asm volatile("" : "+v"(ss) :: "memory"); }
;         ss = xor32_sum(ss);
;         const float rn = rsqrtf(ss * (1.0f / 256.0f) + EPS) * (1.0f - lam_init);
;         u32 go2 = (u32)qrow * (u32)a.ldg + (u32)(a.goff + h * 256 + 8 * g); pinu(go2);
;         u32 oo2 = (u32)qrow * 2048u + (u32)(h * 256 + 8 * g); pinu(oo2);
; #pragma unroll
;         for (int m = 0; m < NM; ++m)
; #pragma unroll
;           for (int bp = 0; bp < 2; ++bp) {
;             u32x2 pk[2];
;             const u32x4 gl = *(const u32x4*)(a.gate + go2 + 32 * m + 16 * bp);
;             const auto q0 = __builtin_amdgcn_permlane32_swap(gl[0], gl[2], false, false);
;             const auto q1 = __builtin_amdgcn_permlane32_swap(gl[1], gl[3], false, false);
;             u32x2 gsel[2]; gsel[0][0] = q0[0]; gsel[0][1] = q1[0]; gsel[1][0] = q0[1]; gsel[1][1] = q1[1];
; #pragma unroll
;             for (int bb = 0; bb < 2; ++bb) {
;               const int b = 2 * bp + bb;
;               const int dv = 32 * m + 8 * b;
;               const u32x2 gu = gsel[bb];
;               const float4 sg = *(const float4*)(a.subln + dv + 4 * g);
;               const float g0 = bflo(gu[0]), g1 = bfhi(gu[0]), g2 = bflo(gu[1]), g3 = bfhi(gu[1]);
;               const float y0 = o[m][4 * b] * rn * sg.x * g0 * __builtin_amdgcn_rcpf(1.f + __expf(-g0));
;               const float y1 = o[m][4 * b + 1] * rn * sg.y * g1 * __builtin_amdgcn_rcpf(1.f + __expf(-g1));
;               const float y2 = o[m][4 * b + 2] * rn * sg.z * g2 * __builtin_amdgcn_rcpf(1.f + __expf(-g2));
;               const float y3 = o[m][4 * b + 3] * rn * sg.w * g3 * __builtin_amdgcn_rcpf(1.f + __expf(-g3));
;               pk[bb][0] = pk2(y0, y1); pk[bb][1] = pk2(y2, y3);
;             }
;             const auto r0 = __builtin_amdgcn_permlane32_swap(pk[0][0], pk[1][0], false, false);
;             const auto r1 = __builtin_amdgcn_permlane32_swap(pk[0][1], pk[1][1], false, false);
;             u32x4 w; w[0] = r0[0]; w[1] = r1[0]; w[2] = r0[1]; w[3] = r1[1];
;             *(u32x4*)(a.og + oo2 + 32 * m + 16 * bp) = w;
;             __builtin_amdgcn_sched_barrier(0);
;           }
	v_pk_fma_f32 v[2:3], v[30:31], v[0:1], v[2:3] op_sel_hi:[1,0,1] neg_lo:[0,0,1] neg_hi:[0,0,1]
	v_pk_fma_f32 v[4:5], v[28:29], v[0:1], v[42:43] op_sel_hi:[1,0,1] neg_lo:[0,0,1] neg_hi:[0,0,1]
	v_pk_fma_f32 v[6:7], v[26:27], v[0:1], v[40:41] op_sel_hi:[1,0,1] neg_lo:[0,0,1] neg_hi:[0,0,1]
	v_add_f32_e32 v0, v44, v12
	v_pk_mul_f32 v[26:27], v[6:7], v[6:7]
	v_add_f32_e32 v0, v0, v13
	v_add_f32_e32 v0, v0, v26
	v_pk_mul_f32 v[28:29], v[4:5], v[4:5]
	v_add_f32_e32 v0, v0, v27
	v_add_f32_e32 v0, v0, v28
	v_pk_mul_f32 v[22:23], v[2:3], v[2:3]
	v_add_f32_e32 v0, v0, v29
	v_add_f32_e32 v0, v0, v22
	v_add_f32_e32 v23, v0, v23
	v_mov_b32_e32 v0, v14
	v_lshlrev_b32_e32 v22, 4, v152
	v_lshl_add_u64 v[12:13], v[0:1], 1, s[40:41]
	global_load_dwordx4 v[24:27], v[12:13], off
	global_load_dwordx4 v[28:31], v22, s[46:47]
	global_load_dwordx4 v[40:43], v22, s[46:47] offset:32
	global_load_dwordx4 v[160:163], v[12:13], off offset:32
	global_load_dwordx4 v[164:167], v[12:13], off offset:64
	global_load_dwordx4 v[168:171], v[12:13], off offset:96
	global_load_dwordx4 v[172:175], v[12:13], off offset:128
	global_load_dwordx4 v[176:179], v[12:13], off offset:160
	global_load_dwordx4 v[180:183], v[12:13], off offset:192
	global_load_dwordx4 v[184:187], v[12:13], off offset:224
	global_load_dwordx4 v[188:191], v[12:13], off offset:256
	global_load_dwordx4 v[192:195], v[12:13], off offset:288
	global_load_dwordx4 v[196:199], v[12:13], off offset:320
	global_load_dwordx4 v[200:203], v[12:13], off offset:352
	global_load_dwordx4 v[204:207], v[12:13], off offset:384
	global_load_dwordx4 v[228:231], v[12:13], off offset:416
	global_load_dwordx4 v[232:235], v[12:13], off offset:448
	global_load_dwordx4 v[236:239], v[12:13], off offset:480
	global_load_dwordx4 v[244:247], v22, s[46:47] offset:64
	global_load_dwordx4 v[248:251], v22, s[46:47] offset:96
	v_mov_b32_e32 v0, v23
	s_nop 1
	v_permlane32_swap_b32_e32 v23, v0
	v_add_f32_e32 v0, v23, v0
	v_fmamk_f32 v0, v0, 0x3b800000, v212
	v_mul_f32_e32 v23, 0x4b800000, v0
	v_cmp_gt_f32_e32 vcc, s72, v0
	s_waitcnt vmcnt(20)
	v_sub_f32_e32 v15, 1.0, v15
	s_waitcnt vmcnt(19)
	v_mov_b32_e32 v152, v27
	v_cndmask_b32_e32 v0, v0, v23, vcc
	v_rsq_f32_e32 v0, v0
	v_permlane32_swap_b32_e32 v25, v152
	v_mul_f32_e32 v23, 0x45800000, v0
	v_cndmask_b32_e32 v0, v0, v23, vcc
	v_mov_b32_e32 v23, v26
	s_nop 1
	v_permlane32_swap_b32_e32 v24, v23
	v_lshlrev_b32_e32 v26, 16, v24
	v_mul_f32_e32 v27, 0xbfb8aa3b, v26
	v_exp_f32_e32 v44, v27
	v_and_b32_e32 v27, 0xffff0000, v24
	v_mul_f32_e32 v45, 0xbfb8aa3b, v27
	v_exp_f32_e32 v45, v45
	v_mul_f32_e32 v0, v15, v0
	v_pk_mul_f32 v[46:47], v[150:151], v[0:1] op_sel_hi:[1,0]
	v_lshlrev_b32_e32 v24, 16, v25
	s_waitcnt vmcnt(18)
	v_pk_mul_f32 v[28:29], v[28:29], v[46:47]
	v_and_b32_e32 v25, 0xffff0000, v25
	v_pk_mul_f32 v[26:27], v[28:29], v[26:27]
	v_add_f32_e32 v28, 1.0, v45
	v_rcp_f32_e32 v45, v28
	v_mul_f32_e32 v28, 0xbfb8aa3b, v24
	v_mul_f32_e32 v29, 0xbfb8aa3b, v25
	v_exp_f32_e32 v28, v28
	v_exp_f32_e32 v29, v29
	v_add_f32_e32 v44, 1.0, v44
	v_rcp_f32_e32 v44, v44
	v_add_f32_e32 v28, 1.0, v28
	v_add_f32_e32 v29, 1.0, v29
	v_rcp_f32_e32 v28, v28
	v_rcp_f32_e32 v29, v29
	v_pk_mul_f32 v[26:27], v[44:45], v[26:27]
	v_pk_mul_f32 v[44:45], v[148:149], v[0:1] op_sel_hi:[1,0]
	v_mov_b32_e32 v15, v1
	v_pk_mul_f32 v[30:31], v[30:31], v[44:45]
	v_pk_mul_f32 v[44:45], v[146:147], v[0:1] op_sel_hi:[1,0]
	v_pk_mul_f32 v[24:25], v[30:31], v[24:25]
	s_waitcnt vmcnt(17)
	v_pk_mul_f32 v[40:41], v[40:41], v[44:45]
	v_pk_mul_f32 v[28:29], v[28:29], v[24:25]
	v_cvt_pk_bf16_f32 v24, v26, v27
	v_lshlrev_b32_e32 v26, 16, v23
	v_mul_f32_e32 v27, 0xbfb8aa3b, v26
	v_exp_f32_e32 v30, v27
	v_and_b32_e32 v27, 0xffff0000, v23
	v_cvt_pk_bf16_f32 v25, v28, v29
	v_lshlrev_b32_e32 v28, 16, v152
	v_add_f32_e32 v23, 1.0, v30
	v_rcp_f32_e32 v30, v23
	v_mul_f32_e32 v23, 0xbfb8aa3b, v27
	v_exp_f32_e32 v23, v23
	v_and_b32_e32 v29, 0xffff0000, v152
	v_pk_mul_f32 v[26:27], v[40:41], v[26:27]
	v_mul_f32_e32 v40, 0xbfb8aa3b, v29
	v_add_f32_e32 v23, 1.0, v23
	v_rcp_f32_e32 v31, v23
	v_mul_f32_e32 v23, 0xbfb8aa3b, v28
	v_exp_f32_e32 v23, v23
	v_exp_f32_e32 v40, v40
	v_pk_mul_f32 v[26:27], v[30:31], v[26:27]
	v_lshl_add_u64 v[14:15], v[14:15], 1, s[24:25]
	v_add_f32_e32 v23, 1.0, v23
	v_rcp_f32_e32 v30, v23
	v_add_f32_e32 v23, 1.0, v40
	v_rcp_f32_e32 v31, v23
	v_pk_mul_f32 v[40:41], v[144:145], v[0:1] op_sel_hi:[1,0]
	v_cvt_pk_bf16_f32 v26, v26, v27
	v_pk_mul_f32 v[40:41], v[42:43], v[40:41]
	s_nop 0
	v_permlane32_swap_b32_e32 v24, v26
	v_pk_mul_f32 v[28:29], v[40:41], v[28:29]
	s_nop 0
	v_pk_mul_f32 v[28:29], v[30:31], v[28:29]
	s_nop 0
	v_cvt_pk_bf16_f32 v27, v28, v29
	s_nop 1
	v_permlane32_swap_b32_e32 v25, v27
	global_store_dwordx4 v[14:15], v[24:27], off
	s_nop 0
	global_load_dwordx4 v[156:159], v22, s[46:47] offset:128
	global_load_dwordx4 v[240:243], v22, s[46:47] offset:160
	s_waitcnt vmcnt(3)
; DI u32 pk2(float a, float b) { f2_t v = {a, b}; bf2_t r = __builtin_convertvector(v, bf2_t); return __builtin_bit_cast(u32, r); }
; DI float bflo(u32 u) { return __uint_as_float(u << 16); }
; DI float bfhi(u32 u) { return __uint_as_float(u & 0xffff0000u); }
; template <bool DIFF>
; DI void attn_phase(const AttnArgs& a, char* lds) {
;     ...
; #pragma unroll
;         for (int m = 0; m < NM; ++m)
; #pragma unroll
;           for (int bp = 0; bp < 2; ++bp) {
;             u32x2 pk[2];
;             const u32x4 gl = *(const u32x4*)(a.gate + go2 + 32 * m + 16 * bp);
;             const auto q0 = __builtin_amdgcn_permlane32_swap(gl[0], gl[2], false, false);
;             const auto q1 = __builtin_amdgcn_permlane32_swap(gl[1], gl[3], false, false);
;             u32x2 gsel[2]; gsel[0][0] = q0[0]; gsel[0][1] = q1[0]; gsel[1][0] = q0[1]; gsel[1][1] = q1[1];
; #pragma unroll
;             for (int bb = 0; bb < 2; ++bb) {
;               const int b = 2 * bp + bb;
;               const int dv = 32 * m + 8 * b;
;               const u32x2 gu = gsel[bb];
;               const float4 sg = *(const float4*)(a.subln + dv + 4 * g);
;               const float g0 = bflo(gu[0]), g1 = bfhi(gu[0]), g2 = bflo(gu[1]), g3 = bfhi(gu[1]);
;               const float y0 = o[m][4 * b] * rn * sg.x * g0 * __builtin_amdgcn_rcpf(1.f + __expf(-g0));
;               const float y1 = o[m][4 * b + 1] * rn * sg.y * g1 * __builtin_amdgcn_rcpf(1.f + __expf(-g1));
;               const float y2 = o[m][4 * b + 2] * rn * sg.z * g2 * __builtin_amdgcn_rcpf(1.f + __expf(-g2));
;               const float y3 = o[m][4 * b + 3] * rn * sg.w * g3 * __builtin_amdgcn_rcpf(1.f + __expf(-g3));
;               pk[bb][0] = pk2(y0, y1); pk[bb][1] = pk2(y2, y3);
;             }
;             const auto r0 = __builtin_amdgcn_permlane32_swap(pk[0][0], pk[1][0], false, false);
;             const auto r1 = __builtin_amdgcn_permlane32_swap(pk[0][1], pk[1][1], false, false);
;             u32x4 w; w[0] = r0[0]; w[1] = r1[0]; w[2] = r0[1]; w[3] = r1[1];
;             *(u32x4*)(a.og + oo2 + 32 * m + 16 * bp) = w;
;             __builtin_amdgcn_sched_barrier(0);
;           }
	v_mov_b32_e32 v24, v160
	v_mov_b32_e32 v25, v161
	v_mov_b32_e32 v26, v162
	v_mov_b32_e32 v27, v163
	v_mov_b32_e32 v28, v244
	v_mov_b32_e32 v29, v245
	v_mov_b32_e32 v30, v246
	v_mov_b32_e32 v31, v247
	v_mov_b32_e32 v40, v248
	v_mov_b32_e32 v41, v249
	v_mov_b32_e32 v42, v250
	v_mov_b32_e32 v43, v251
	v_pk_mul_f32 v[44:45], v[136:137], v[0:1] op_sel_hi:[1,0]
	v_pk_mul_f32 v[136:137], v[140:141], v[0:1] op_sel_hi:[1,0]
	v_pk_mul_f32 v[46:47], v[138:139], v[0:1] op_sel_hi:[1,0]
	v_pk_mul_f32 v[138:139], v[142:143], v[0:1] op_sel_hi:[1,0]
	s_nop 0
	v_mov_b32_e32 v23, v26
	v_mov_b32_e32 v140, v27
	s_nop 0
	v_permlane32_swap_b32_e32 v24, v23
	v_permlane32_swap_b32_e32 v25, v140
	s_nop 0
	v_pk_mul_f32 v[26:27], v[44:45], v[28:29]
	v_pk_mul_f32 v[28:29], v[46:47], v[30:31]
	s_nop 0
	v_pk_mul_f32 v[30:31], v[136:137], v[40:41]
	v_pk_mul_f32 v[40:41], v[138:139], v[42:43]
	v_lshlrev_b32_e32 v42, 16, v24
	v_and_b32_e32 v43, 0xffff0000, v24
	v_lshlrev_b32_e32 v24, 16, v25
	v_and_b32_e32 v25, 0xffff0000, v25
	v_lshlrev_b32_e32 v44, 16, v23
	v_and_b32_e32 v45, 0xffff0000, v23
	v_lshlrev_b32_e32 v46, 16, v140
	v_and_b32_e32 v47, 0xffff0000, v140
	v_mul_f32_e32 v23, 0xbfb8aa3b, v42
	v_pk_mul_f32 v[26:27], v[26:27], v[42:43]
	v_mul_f32_e32 v42, 0xbfb8aa3b, v43
	v_mul_f32_e32 v43, 0xbfb8aa3b, v24
	v_pk_mul_f32 v[28:29], v[28:29], v[24:25]
	v_mul_f32_e32 v136, 0xbfb8aa3b, v25
	v_mul_f32_e32 v137, 0xbfb8aa3b, v44
	v_pk_mul_f32 v[24:25], v[30:31], v[44:45]
	v_mul_f32_e32 v44, 0xbfb8aa3b, v45
	v_mul_f32_e32 v45, 0xbfb8aa3b, v46
	v_pk_mul_f32 v[30:31], v[40:41], v[46:47]
	v_mul_f32_e32 v40, 0xbfb8aa3b, v47
	v_exp_f32_e32 v23, v23
	v_exp_f32_e32 v41, v42
	v_exp_f32_e32 v42, v43
	v_exp_f32_e32 v43, v136
	v_exp_f32_e32 v46, v137
	v_exp_f32_e32 v44, v44
	v_exp_f32_e32 v45, v45
	v_exp_f32_e32 v40, v40
	v_add_f32_e32 v23, 1.0, v23
	v_add_f32_e32 v41, 1.0, v41
	v_add_f32_e32 v42, 1.0, v42
	v_add_f32_e32 v43, 1.0, v43
	v_add_f32_e32 v46, 1.0, v46
	v_add_f32_e32 v47, 1.0, v44
	v_add_f32_e32 v136, 1.0, v45
	v_add_f32_e32 v137, 1.0, v40
	v_rcp_f32_e32 v40, v23
	v_rcp_f32_e32 v41, v41
	v_rcp_f32_e32 v42, v42
	v_rcp_f32_e32 v43, v43
	v_rcp_f32_e32 v44, v46
	v_rcp_f32_e32 v45, v47
	v_rcp_f32_e32 v46, v136
	v_rcp_f32_e32 v47, v137
	v_pk_mul_f32 v[26:27], v[26:27], v[40:41]
	v_pk_mul_f32 v[28:29], v[28:29], v[42:43]
	v_pk_mul_f32 v[40:41], v[44:45], v[24:25]
	v_pk_mul_f32 v[30:31], v[46:47], v[30:31]
	v_cvt_pk_bf16_f32 v24, v26, v27
	v_cvt_pk_bf16_f32 v25, v28, v29
	v_cvt_pk_bf16_f32 v26, v40, v41
	v_cvt_pk_bf16_f32 v27, v30, v31
	s_nop 0
	v_permlane32_swap_b32_e32 v24, v26
	v_permlane32_swap_b32_e32 v25, v27
	global_store_dwordx4 v[14:15], v[24:27], off offset:32
	s_nop 0
	global_load_dwordx4 v[244:247], v22, s[46:47] offset:192
	global_load_dwordx4 v[248:251], v22, s[46:47] offset:224
	s_waitcnt vmcnt(3)
	v_mov_b32_e32 v24, v164
	v_mov_b32_e32 v25, v165
	v_mov_b32_e32 v26, v166
	v_mov_b32_e32 v27, v167
	v_mov_b32_e32 v28, v156
	v_mov_b32_e32 v29, v157
	v_mov_b32_e32 v30, v158
	v_mov_b32_e32 v31, v159
	v_mov_b32_e32 v40, v240
	v_mov_b32_e32 v41, v241
	v_mov_b32_e32 v42, v242
	v_mov_b32_e32 v43, v243
	v_pk_mul_f32 v[46:47], v[132:133], v[0:1] op_sel_hi:[1,0]
	v_pk_mul_f32 v[44:45], v[134:135], v[0:1] op_sel_hi:[1,0]
	v_pk_mul_f32 v[130:131], v[130:131], v[0:1] op_sel_hi:[1,0]
	v_pk_mul_f32 v[128:129], v[128:129], v[0:1] op_sel_hi:[1,0]
	s_nop 0
	v_mov_b32_e32 v23, v26
	v_mov_b32_e32 v132, v27
	s_nop 0
	v_permlane32_swap_b32_e32 v24, v23
	v_permlane32_swap_b32_e32 v25, v132
	s_nop 0
	v_pk_mul_f32 v[26:27], v[44:45], v[28:29]
	v_pk_mul_f32 v[28:29], v[46:47], v[30:31]
	s_nop 0
	v_pk_mul_f32 v[30:31], v[130:131], v[40:41]
	v_pk_mul_f32 v[40:41], v[128:129], v[42:43]
	v_lshlrev_b32_e32 v42, 16, v24
	v_and_b32_e32 v43, 0xffff0000, v24
	v_lshlrev_b32_e32 v24, 16, v25
	v_and_b32_e32 v25, 0xffff0000, v25
	v_lshlrev_b32_e32 v44, 16, v23
	v_and_b32_e32 v45, 0xffff0000, v23
	v_lshlrev_b32_e32 v46, 16, v132
	v_and_b32_e32 v47, 0xffff0000, v132
	v_mul_f32_e32 v23, 0xbfb8aa3b, v42
	v_pk_mul_f32 v[26:27], v[26:27], v[42:43]
	v_mul_f32_e32 v42, 0xbfb8aa3b, v43
	v_mul_f32_e32 v43, 0xbfb8aa3b, v24
	v_pk_mul_f32 v[28:29], v[28:29], v[24:25]
	v_mul_f32_e32 v128, 0xbfb8aa3b, v25
	v_mul_f32_e32 v129, 0xbfb8aa3b, v44
	v_pk_mul_f32 v[24:25], v[30:31], v[44:45]
	v_mul_f32_e32 v44, 0xbfb8aa3b, v45
	v_mul_f32_e32 v45, 0xbfb8aa3b, v46
	v_pk_mul_f32 v[30:31], v[40:41], v[46:47]
	v_mul_f32_e32 v40, 0xbfb8aa3b, v47
	v_exp_f32_e32 v23, v23
	v_exp_f32_e32 v41, v42
	v_exp_f32_e32 v42, v43
	v_exp_f32_e32 v43, v128
	v_exp_f32_e32 v46, v129
	v_exp_f32_e32 v44, v44
	v_exp_f32_e32 v45, v45
	v_exp_f32_e32 v40, v40
	v_add_f32_e32 v23, 1.0, v23
	v_add_f32_e32 v41, 1.0, v41
	v_add_f32_e32 v42, 1.0, v42
	v_add_f32_e32 v43, 1.0, v43
	v_add_f32_e32 v46, 1.0, v46
	v_add_f32_e32 v47, 1.0, v44
	v_add_f32_e32 v128, 1.0, v45
	v_add_f32_e32 v129, 1.0, v40
	v_rcp_f32_e32 v40, v23
	v_rcp_f32_e32 v41, v41
	v_rcp_f32_e32 v42, v42
	v_rcp_f32_e32 v43, v43
	v_rcp_f32_e32 v44, v46
	v_rcp_f32_e32 v45, v47
	v_rcp_f32_e32 v46, v128
	v_rcp_f32_e32 v47, v129
	v_pk_mul_f32 v[26:27], v[26:27], v[40:41]
	v_pk_mul_f32 v[28:29], v[28:29], v[42:43]
	v_pk_mul_f32 v[40:41], v[44:45], v[24:25]
	v_pk_mul_f32 v[30:31], v[46:47], v[30:31]
	v_cvt_pk_bf16_f32 v24, v26, v27
	v_cvt_pk_bf16_f32 v25, v28, v29
	v_cvt_pk_bf16_f32 v26, v40, v41
	v_cvt_pk_bf16_f32 v27, v30, v31
	s_nop 0
	v_permlane32_swap_b32_e32 v24, v26
	v_permlane32_swap_b32_e32 v25, v27
	global_store_dwordx4 v[14:15], v[24:27], off offset:64
	s_nop 0
	global_load_dwordx4 v[156:159], v22, s[46:47] offset:256
	global_load_dwordx4 v[240:243], v22, s[46:47] offset:288
	s_waitcnt vmcnt(3)
; DI u32 pk2(float a, float b) { f2_t v = {a, b}; bf2_t r = __builtin_convertvector(v, bf2_t); return __builtin_bit_cast(u32, r); }
; DI float bflo(u32 u) { return __uint_as_float(u << 16); }
; DI float bfhi(u32 u) { return __uint_as_float(u & 0xffff0000u); }
; template <bool DIFF>
; DI void attn_phase(const AttnArgs& a, char* lds) {
;     ...
; #pragma unroll
;         for (int m = 0; m < NM; ++m)
; #pragma unroll
;           for (int bp = 0; bp < 2; ++bp) {
;             u32x2 pk[2];
;             const u32x4 gl = *(const u32x4*)(a.gate + go2 + 32 * m + 16 * bp);
;             const auto q0 = __builtin_amdgcn_permlane32_swap(gl[0], gl[2], false, false);
;             const auto q1 = __builtin_amdgcn_permlane32_swap(gl[1], gl[3], false, false);
;             u32x2 gsel[2]; gsel[0][0] = q0[0]; gsel[0][1] = q1[0]; gsel[1][0] = q0[1]; gsel[1][1] = q1[1];
; #pragma unroll
;             for (int bb = 0; bb < 2; ++bb) {
;               const int b = 2 * bp + bb;
;               const int dv = 32 * m + 8 * b;
;               const u32x2 gu = gsel[bb];
;               const float4 sg = *(const float4*)(a.subln + dv + 4 * g);
;               const float g0 = bflo(gu[0]), g1 = bfhi(gu[0]), g2 = bflo(gu[1]), g3 = bfhi(gu[1]);
;               const float y0 = o[m][4 * b] * rn * sg.x * g0 * __builtin_amdgcn_rcpf(1.f + __expf(-g0));
;               const float y1 = o[m][4 * b + 1] * rn * sg.y * g1 * __builtin_amdgcn_rcpf(1.f + __expf(-g1));
;               const float y2 = o[m][4 * b + 2] * rn * sg.z * g2 * __builtin_amdgcn_rcpf(1.f + __expf(-g2));
;               const float y3 = o[m][4 * b + 3] * rn * sg.w * g3 * __builtin_amdgcn_rcpf(1.f + __expf(-g3));
;               pk[bb][0] = pk2(y0, y1); pk[bb][1] = pk2(y2, y3);
;             }
;             const auto r0 = __builtin_amdgcn_permlane32_swap(pk[0][0], pk[1][0], false, false);
;             const auto r1 = __builtin_amdgcn_permlane32_swap(pk[0][1], pk[1][1], false, false);
;             u32x4 w; w[0] = r0[0]; w[1] = r1[0]; w[2] = r0[1]; w[3] = r1[1];
;             *(u32x4*)(a.og + oo2 + 32 * m + 16 * bp) = w;
;             __builtin_amdgcn_sched_barrier(0);
;           }
	v_mov_b32_e32 v24, v168
	v_mov_b32_e32 v25, v169
	v_mov_b32_e32 v26, v170
	v_mov_b32_e32 v27, v171
	v_mov_b32_e32 v28, v244
	v_mov_b32_e32 v29, v245
	v_mov_b32_e32 v30, v246
	v_mov_b32_e32 v31, v247
	v_mov_b32_e32 v40, v248
	v_mov_b32_e32 v41, v249
	v_mov_b32_e32 v42, v250
	v_mov_b32_e32 v43, v251
	v_pk_mul_f32 v[44:45], v[120:121], v[0:1] op_sel_hi:[1,0]
	v_pk_mul_f32 v[120:121], v[124:125], v[0:1] op_sel_hi:[1,0]
	v_pk_mul_f32 v[46:47], v[122:123], v[0:1] op_sel_hi:[1,0]
	v_pk_mul_f32 v[122:123], v[126:127], v[0:1] op_sel_hi:[1,0]
	s_nop 0
	v_mov_b32_e32 v23, v26
	v_mov_b32_e32 v124, v27
	s_nop 0
	v_permlane32_swap_b32_e32 v24, v23
	v_permlane32_swap_b32_e32 v25, v124
	s_nop 0
	v_pk_mul_f32 v[26:27], v[44:45], v[28:29]
	v_pk_mul_f32 v[28:29], v[46:47], v[30:31]
	s_nop 0
	v_pk_mul_f32 v[30:31], v[120:121], v[40:41]
	v_pk_mul_f32 v[40:41], v[122:123], v[42:43]
	v_lshlrev_b32_e32 v42, 16, v24
	v_and_b32_e32 v43, 0xffff0000, v24
	v_lshlrev_b32_e32 v24, 16, v25
	v_and_b32_e32 v25, 0xffff0000, v25
	v_lshlrev_b32_e32 v44, 16, v23
	v_and_b32_e32 v45, 0xffff0000, v23
	v_lshlrev_b32_e32 v46, 16, v124
	v_and_b32_e32 v47, 0xffff0000, v124
	v_mul_f32_e32 v23, 0xbfb8aa3b, v42
	v_pk_mul_f32 v[26:27], v[26:27], v[42:43]
	v_mul_f32_e32 v42, 0xbfb8aa3b, v43
	v_mul_f32_e32 v43, 0xbfb8aa3b, v24
	v_pk_mul_f32 v[28:29], v[28:29], v[24:25]
	v_mul_f32_e32 v120, 0xbfb8aa3b, v25
	v_mul_f32_e32 v121, 0xbfb8aa3b, v44
	v_pk_mul_f32 v[24:25], v[30:31], v[44:45]
	v_mul_f32_e32 v44, 0xbfb8aa3b, v45
	v_mul_f32_e32 v45, 0xbfb8aa3b, v46
	v_pk_mul_f32 v[30:31], v[40:41], v[46:47]
	v_mul_f32_e32 v40, 0xbfb8aa3b, v47
	v_exp_f32_e32 v23, v23
	v_exp_f32_e32 v41, v42
	v_exp_f32_e32 v42, v43
	v_exp_f32_e32 v43, v120
	v_exp_f32_e32 v46, v121
	v_exp_f32_e32 v44, v44
	v_exp_f32_e32 v45, v45
	v_exp_f32_e32 v40, v40
	v_add_f32_e32 v23, 1.0, v23
	v_add_f32_e32 v41, 1.0, v41
	v_add_f32_e32 v42, 1.0, v42
	v_add_f32_e32 v43, 1.0, v43
	v_add_f32_e32 v46, 1.0, v46
	v_add_f32_e32 v47, 1.0, v44
	v_add_f32_e32 v120, 1.0, v45
	v_add_f32_e32 v121, 1.0, v40
	v_rcp_f32_e32 v40, v23
	v_rcp_f32_e32 v41, v41
	v_rcp_f32_e32 v42, v42
	v_rcp_f32_e32 v43, v43
	v_rcp_f32_e32 v44, v46
	v_rcp_f32_e32 v45, v47
	v_rcp_f32_e32 v46, v120
	v_rcp_f32_e32 v47, v121
	v_pk_mul_f32 v[26:27], v[26:27], v[40:41]
	v_pk_mul_f32 v[28:29], v[28:29], v[42:43]
	v_pk_mul_f32 v[40:41], v[44:45], v[24:25]
	v_pk_mul_f32 v[30:31], v[46:47], v[30:31]
	v_cvt_pk_bf16_f32 v24, v26, v27
	v_cvt_pk_bf16_f32 v25, v28, v29
	v_cvt_pk_bf16_f32 v26, v40, v41
	v_cvt_pk_bf16_f32 v27, v30, v31
	s_nop 0
	v_permlane32_swap_b32_e32 v24, v26
	v_permlane32_swap_b32_e32 v25, v27
	global_store_dwordx4 v[14:15], v[24:27], off offset:96
	s_nop 0
	global_load_dwordx4 v[244:247], v22, s[46:47] offset:320
	global_load_dwordx4 v[248:251], v22, s[46:47] offset:352
	s_waitcnt vmcnt(3)
	v_mov_b32_e32 v24, v172
	v_mov_b32_e32 v25, v173
	v_mov_b32_e32 v26, v174
	v_mov_b32_e32 v27, v175
	v_mov_b32_e32 v28, v156
	v_mov_b32_e32 v29, v157
	v_mov_b32_e32 v30, v158
	v_mov_b32_e32 v31, v159
	v_mov_b32_e32 v40, v240
	v_mov_b32_e32 v41, v241
	v_mov_b32_e32 v42, v242
	v_mov_b32_e32 v43, v243
	v_pk_mul_f32 v[46:47], v[116:117], v[0:1] op_sel_hi:[1,0]
	v_pk_mul_f32 v[44:45], v[118:119], v[0:1] op_sel_hi:[1,0]
	v_pk_mul_f32 v[114:115], v[114:115], v[0:1] op_sel_hi:[1,0]
	v_pk_mul_f32 v[112:113], v[112:113], v[0:1] op_sel_hi:[1,0]
	s_nop 0
	v_mov_b32_e32 v23, v26
	v_mov_b32_e32 v116, v27
	s_nop 0
	v_permlane32_swap_b32_e32 v24, v23
	v_permlane32_swap_b32_e32 v25, v116
	s_nop 0
	v_pk_mul_f32 v[26:27], v[44:45], v[28:29]
	v_pk_mul_f32 v[28:29], v[46:47], v[30:31]
	s_nop 0
	v_pk_mul_f32 v[30:31], v[114:115], v[40:41]
	v_pk_mul_f32 v[40:41], v[112:113], v[42:43]
	v_lshlrev_b32_e32 v42, 16, v24
	v_and_b32_e32 v43, 0xffff0000, v24
	v_lshlrev_b32_e32 v24, 16, v25
	v_and_b32_e32 v25, 0xffff0000, v25
	v_lshlrev_b32_e32 v44, 16, v23
	v_and_b32_e32 v45, 0xffff0000, v23
	v_lshlrev_b32_e32 v46, 16, v116
	v_and_b32_e32 v47, 0xffff0000, v116
	v_mul_f32_e32 v23, 0xbfb8aa3b, v42
	v_pk_mul_f32 v[26:27], v[26:27], v[42:43]
	v_mul_f32_e32 v42, 0xbfb8aa3b, v43
	v_mul_f32_e32 v43, 0xbfb8aa3b, v24
	v_pk_mul_f32 v[28:29], v[28:29], v[24:25]
	v_mul_f32_e32 v112, 0xbfb8aa3b, v25
	v_mul_f32_e32 v113, 0xbfb8aa3b, v44
	v_pk_mul_f32 v[24:25], v[30:31], v[44:45]
	v_mul_f32_e32 v44, 0xbfb8aa3b, v45
	v_mul_f32_e32 v45, 0xbfb8aa3b, v46
	v_pk_mul_f32 v[30:31], v[40:41], v[46:47]
	v_mul_f32_e32 v40, 0xbfb8aa3b, v47
	v_exp_f32_e32 v23, v23
	v_exp_f32_e32 v41, v42
	v_exp_f32_e32 v42, v43
	v_exp_f32_e32 v43, v112
	v_exp_f32_e32 v46, v113
	v_exp_f32_e32 v44, v44
	v_exp_f32_e32 v45, v45
	v_exp_f32_e32 v40, v40
	v_add_f32_e32 v23, 1.0, v23
	v_add_f32_e32 v41, 1.0, v41
	v_add_f32_e32 v42, 1.0, v42
	v_add_f32_e32 v43, 1.0, v43
	v_add_f32_e32 v46, 1.0, v46
	v_add_f32_e32 v47, 1.0, v44
	v_add_f32_e32 v112, 1.0, v45
	v_add_f32_e32 v113, 1.0, v40
	v_rcp_f32_e32 v40, v23
	v_rcp_f32_e32 v41, v41
	v_rcp_f32_e32 v42, v42
	v_rcp_f32_e32 v43, v43
	v_rcp_f32_e32 v44, v46
	v_rcp_f32_e32 v45, v47
	v_rcp_f32_e32 v46, v112
	v_rcp_f32_e32 v47, v113
	v_pk_mul_f32 v[26:27], v[26:27], v[40:41]
	v_pk_mul_f32 v[28:29], v[28:29], v[42:43]
	v_pk_mul_f32 v[40:41], v[44:45], v[24:25]
	v_pk_mul_f32 v[30:31], v[46:47], v[30:31]
	v_cvt_pk_bf16_f32 v24, v26, v27
	v_cvt_pk_bf16_f32 v25, v28, v29
	v_cvt_pk_bf16_f32 v26, v40, v41
	v_cvt_pk_bf16_f32 v27, v30, v31
	s_nop 0
	v_permlane32_swap_b32_e32 v24, v26
	v_permlane32_swap_b32_e32 v25, v27
	global_store_dwordx4 v[14:15], v[24:27], off offset:128
	s_nop 0
	global_load_dwordx4 v[156:159], v22, s[46:47] offset:384
	global_load_dwordx4 v[240:243], v22, s[46:47] offset:416
	s_waitcnt vmcnt(3)
; DI u32 pk2(float a, float b) { f2_t v = {a, b}; bf2_t r = __builtin_convertvector(v, bf2_t); return __builtin_bit_cast(u32, r); }
; DI float bflo(u32 u) { return __uint_as_float(u << 16); }
; DI float bfhi(u32 u) { return __uint_as_float(u & 0xffff0000u); }
; template <bool DIFF>
; DI void attn_phase(const AttnArgs& a, char* lds) {
;     ...
; #pragma unroll
;         for (int m = 0; m < NM; ++m)
; #pragma unroll
;           for (int bp = 0; bp < 2; ++bp) {
;             u32x2 pk[2];
;             const u32x4 gl = *(const u32x4*)(a.gate + go2 + 32 * m + 16 * bp);
;             const auto q0 = __builtin_amdgcn_permlane32_swap(gl[0], gl[2], false, false);
;             const auto q1 = __builtin_amdgcn_permlane32_swap(gl[1], gl[3], false, false);
;             u32x2 gsel[2]; gsel[0][0] = q0[0]; gsel[0][1] = q1[0]; gsel[1][0] = q0[1]; gsel[1][1] = q1[1];
; #pragma unroll
;             for (int bb = 0; bb < 2; ++bb) {
;               const int b = 2 * bp + bb;
;               const int dv = 32 * m + 8 * b;
;               const u32x2 gu = gsel[bb];
;               const float4 sg = *(const float4*)(a.subln + dv + 4 * g);
;               const float g0 = bflo(gu[0]), g1 = bfhi(gu[0]), g2 = bflo(gu[1]), g3 = bfhi(gu[1]);
;               const float y0 = o[m][4 * b] * rn * sg.x * g0 * __builtin_amdgcn_rcpf(1.f + __expf(-g0));
;               const float y1 = o[m][4 * b + 1] * rn * sg.y * g1 * __builtin_amdgcn_rcpf(1.f + __expf(-g1));
;               const float y2 = o[m][4 * b + 2] * rn * sg.z * g2 * __builtin_amdgcn_rcpf(1.f + __expf(-g2));
;               const float y3 = o[m][4 * b + 3] * rn * sg.w * g3 * __builtin_amdgcn_rcpf(1.f + __expf(-g3));
;               pk[bb][0] = pk2(y0, y1); pk[bb][1] = pk2(y2, y3);
;             }
;             const auto r0 = __builtin_amdgcn_permlane32_swap(pk[0][0], pk[1][0], false, false);
;             const auto r1 = __builtin_amdgcn_permlane32_swap(pk[0][1], pk[1][1], false, false);
;             u32x4 w; w[0] = r0[0]; w[1] = r1[0]; w[2] = r0[1]; w[3] = r1[1];
;             *(u32x4*)(a.og + oo2 + 32 * m + 16 * bp) = w;
;             __builtin_amdgcn_sched_barrier(0);
;           }
	v_mov_b32_e32 v24, v176
	v_mov_b32_e32 v25, v177
	v_mov_b32_e32 v26, v178
	v_mov_b32_e32 v27, v179
	v_mov_b32_e32 v28, v244
	v_mov_b32_e32 v29, v245
	v_mov_b32_e32 v30, v246
	v_mov_b32_e32 v31, v247
	v_mov_b32_e32 v40, v248
	v_mov_b32_e32 v41, v249
	v_mov_b32_e32 v42, v250
	v_mov_b32_e32 v43, v251
	v_pk_mul_f32 v[44:45], v[104:105], v[0:1] op_sel_hi:[1,0]
	v_pk_mul_f32 v[104:105], v[108:109], v[0:1] op_sel_hi:[1,0]
	v_pk_mul_f32 v[46:47], v[106:107], v[0:1] op_sel_hi:[1,0]
	v_pk_mul_f32 v[106:107], v[110:111], v[0:1] op_sel_hi:[1,0]
	s_nop 0
	v_mov_b32_e32 v23, v26
	v_mov_b32_e32 v108, v27
	s_nop 0
	v_permlane32_swap_b32_e32 v24, v23
	v_permlane32_swap_b32_e32 v25, v108
	s_nop 0
	v_pk_mul_f32 v[26:27], v[44:45], v[28:29]
	v_pk_mul_f32 v[28:29], v[46:47], v[30:31]
	s_nop 0
	v_pk_mul_f32 v[30:31], v[104:105], v[40:41]
	v_pk_mul_f32 v[40:41], v[106:107], v[42:43]
	v_lshlrev_b32_e32 v42, 16, v24
	v_and_b32_e32 v43, 0xffff0000, v24
	v_lshlrev_b32_e32 v24, 16, v25
	v_and_b32_e32 v25, 0xffff0000, v25
	v_lshlrev_b32_e32 v44, 16, v23
	v_and_b32_e32 v45, 0xffff0000, v23
	v_lshlrev_b32_e32 v46, 16, v108
	v_and_b32_e32 v47, 0xffff0000, v108
	v_mul_f32_e32 v23, 0xbfb8aa3b, v42
	v_pk_mul_f32 v[26:27], v[26:27], v[42:43]
	v_mul_f32_e32 v42, 0xbfb8aa3b, v43
	v_mul_f32_e32 v43, 0xbfb8aa3b, v24
	v_pk_mul_f32 v[28:29], v[28:29], v[24:25]
	v_mul_f32_e32 v104, 0xbfb8aa3b, v25
	v_mul_f32_e32 v105, 0xbfb8aa3b, v44
	v_pk_mul_f32 v[24:25], v[30:31], v[44:45]
	v_mul_f32_e32 v44, 0xbfb8aa3b, v45
	v_mul_f32_e32 v45, 0xbfb8aa3b, v46
	v_pk_mul_f32 v[30:31], v[40:41], v[46:47]
	v_mul_f32_e32 v40, 0xbfb8aa3b, v47
	v_exp_f32_e32 v23, v23
	v_exp_f32_e32 v41, v42
	v_exp_f32_e32 v42, v43
	v_exp_f32_e32 v43, v104
	v_exp_f32_e32 v46, v105
	v_exp_f32_e32 v44, v44
	v_exp_f32_e32 v45, v45
	v_exp_f32_e32 v40, v40
	v_add_f32_e32 v23, 1.0, v23
	v_add_f32_e32 v41, 1.0, v41
	v_add_f32_e32 v42, 1.0, v42
	v_add_f32_e32 v43, 1.0, v43
	v_add_f32_e32 v46, 1.0, v46
	v_add_f32_e32 v47, 1.0, v44
	v_add_f32_e32 v104, 1.0, v45
	v_add_f32_e32 v105, 1.0, v40
	v_rcp_f32_e32 v40, v23
	v_rcp_f32_e32 v41, v41
	v_rcp_f32_e32 v42, v42
	v_rcp_f32_e32 v43, v43
	v_rcp_f32_e32 v44, v46
	v_rcp_f32_e32 v45, v47
	v_rcp_f32_e32 v46, v104
	v_rcp_f32_e32 v47, v105
	v_pk_mul_f32 v[26:27], v[26:27], v[40:41]
	v_pk_mul_f32 v[28:29], v[28:29], v[42:43]
	v_pk_mul_f32 v[40:41], v[44:45], v[24:25]
	v_pk_mul_f32 v[30:31], v[46:47], v[30:31]
	v_cvt_pk_bf16_f32 v24, v26, v27
	v_cvt_pk_bf16_f32 v25, v28, v29
	v_cvt_pk_bf16_f32 v26, v40, v41
	v_cvt_pk_bf16_f32 v27, v30, v31
	s_nop 0
	v_permlane32_swap_b32_e32 v24, v26
	v_permlane32_swap_b32_e32 v25, v27
	global_store_dwordx4 v[14:15], v[24:27], off offset:160
	s_nop 0
	global_load_dwordx4 v[244:247], v22, s[46:47] offset:448
	global_load_dwordx4 v[248:251], v22, s[46:47] offset:480
	s_waitcnt vmcnt(3)
	v_mov_b32_e32 v24, v180
	v_mov_b32_e32 v25, v181
	v_mov_b32_e32 v26, v182
	v_mov_b32_e32 v27, v183
	v_mov_b32_e32 v28, v156
	v_mov_b32_e32 v29, v157
	v_mov_b32_e32 v30, v158
	v_mov_b32_e32 v31, v159
	v_mov_b32_e32 v40, v240
	v_mov_b32_e32 v41, v241
	v_mov_b32_e32 v42, v242
	v_mov_b32_e32 v43, v243
	v_pk_mul_f32 v[46:47], v[100:101], v[0:1] op_sel_hi:[1,0]
	v_pk_mul_f32 v[44:45], v[102:103], v[0:1] op_sel_hi:[1,0]
	v_pk_mul_f32 v[98:99], v[98:99], v[0:1] op_sel_hi:[1,0]
	v_pk_mul_f32 v[96:97], v[96:97], v[0:1] op_sel_hi:[1,0]
	s_nop 0
	v_mov_b32_e32 v23, v26
	v_mov_b32_e32 v100, v27
	s_nop 0
	v_permlane32_swap_b32_e32 v24, v23
	v_permlane32_swap_b32_e32 v25, v100
	s_nop 0
	v_pk_mul_f32 v[26:27], v[44:45], v[28:29]
	v_pk_mul_f32 v[28:29], v[46:47], v[30:31]
	s_nop 0
	v_pk_mul_f32 v[30:31], v[98:99], v[40:41]
	v_pk_mul_f32 v[40:41], v[96:97], v[42:43]
	v_lshlrev_b32_e32 v42, 16, v24
	v_and_b32_e32 v43, 0xffff0000, v24
	v_lshlrev_b32_e32 v24, 16, v25
	v_and_b32_e32 v25, 0xffff0000, v25
	v_lshlrev_b32_e32 v44, 16, v23
	v_and_b32_e32 v45, 0xffff0000, v23
	v_lshlrev_b32_e32 v46, 16, v100
	v_and_b32_e32 v47, 0xffff0000, v100
	v_mul_f32_e32 v23, 0xbfb8aa3b, v42
	v_pk_mul_f32 v[26:27], v[26:27], v[42:43]
	v_mul_f32_e32 v42, 0xbfb8aa3b, v43
	v_mul_f32_e32 v43, 0xbfb8aa3b, v24
	v_pk_mul_f32 v[28:29], v[28:29], v[24:25]
	v_mul_f32_e32 v96, 0xbfb8aa3b, v25
	v_mul_f32_e32 v97, 0xbfb8aa3b, v44
	v_pk_mul_f32 v[24:25], v[30:31], v[44:45]
	v_mul_f32_e32 v44, 0xbfb8aa3b, v45
	v_mul_f32_e32 v45, 0xbfb8aa3b, v46
	v_pk_mul_f32 v[30:31], v[40:41], v[46:47]
	v_mul_f32_e32 v40, 0xbfb8aa3b, v47
	v_exp_f32_e32 v23, v23
	v_exp_f32_e32 v41, v42
	v_exp_f32_e32 v42, v43
	v_exp_f32_e32 v43, v96
	v_exp_f32_e32 v46, v97
	v_exp_f32_e32 v44, v44
	v_exp_f32_e32 v45, v45
	v_exp_f32_e32 v40, v40
	v_add_f32_e32 v23, 1.0, v23
	v_add_f32_e32 v41, 1.0, v41
	v_add_f32_e32 v42, 1.0, v42
	v_add_f32_e32 v43, 1.0, v43
	v_add_f32_e32 v46, 1.0, v46
	v_add_f32_e32 v47, 1.0, v44
	v_add_f32_e32 v96, 1.0, v45
	v_add_f32_e32 v97, 1.0, v40
	v_rcp_f32_e32 v40, v23
	v_rcp_f32_e32 v41, v41
	v_rcp_f32_e32 v42, v42
	v_rcp_f32_e32 v43, v43
	v_rcp_f32_e32 v44, v46
	v_rcp_f32_e32 v45, v47
	v_rcp_f32_e32 v46, v96
	v_rcp_f32_e32 v47, v97
	v_pk_mul_f32 v[26:27], v[26:27], v[40:41]
	v_pk_mul_f32 v[28:29], v[28:29], v[42:43]
	v_pk_mul_f32 v[40:41], v[44:45], v[24:25]
	v_pk_mul_f32 v[30:31], v[46:47], v[30:31]
	v_cvt_pk_bf16_f32 v24, v26, v27
	v_cvt_pk_bf16_f32 v25, v28, v29
	v_cvt_pk_bf16_f32 v26, v40, v41
	v_cvt_pk_bf16_f32 v27, v30, v31
	s_nop 0
	v_permlane32_swap_b32_e32 v24, v26
	v_permlane32_swap_b32_e32 v25, v27
	global_store_dwordx4 v[14:15], v[24:27], off offset:192
	s_nop 0
	global_load_dwordx4 v[156:159], v22, s[46:47] offset:512
	global_load_dwordx4 v[240:243], v22, s[46:47] offset:544
	s_waitcnt vmcnt(3)
; DI u32 pk2(float a, float b) { f2_t v = {a, b}; bf2_t r = __builtin_convertvector(v, bf2_t); return __builtin_bit_cast(u32, r); }
; DI float bflo(u32 u) { return __uint_as_float(u << 16); }
; DI float bfhi(u32 u) { return __uint_as_float(u & 0xffff0000u); }
; template <bool DIFF>
; DI void attn_phase(const AttnArgs& a, char* lds) {
;     ...
;         for (int m = 0; m < NM; ++m)
; #pragma unroll
;           for (int bp = 0; bp < 2; ++bp) {
;             u32x2 pk[2];
;             const u32x4 gl = *(const u32x4*)(a.gate + go2 + 32 * m + 16 * bp);
;             const auto q0 = __builtin_amdgcn_permlane32_swap(gl[0], gl[2], false, false);
;             const auto q1 = __builtin_amdgcn_permlane32_swap(gl[1], gl[3], false, false);
;             u32x2 gsel[2]; gsel[0][0] = q0[0]; gsel[0][1] = q1[0]; gsel[1][0] = q0[1]; gsel[1][1] = q1[1];
; #pragma unroll
;             for (int bb = 0; bb < 2; ++bb) {
;               const int b = 2 * bp + bb;
;               const int dv = 32 * m + 8 * b;
;               const u32x2 gu = gsel[bb];
;               const float4 sg = *(const float4*)(a.subln + dv + 4 * g);
;               const float g0 = bflo(gu[0]), g1 = bfhi(gu[0]), g2 = bflo(gu[1]), g3 = bfhi(gu[1]);
;               const float y0 = o[m][4 * b] * rn * sg.x * g0 * __builtin_amdgcn_rcpf(1.f + __expf(-g0));
;               const float y1 = o[m][4 * b + 1] * rn * sg.y * g1 * __builtin_amdgcn_rcpf(1.f + __expf(-g1));
;               const float y2 = o[m][4 * b + 2] * rn * sg.z * g2 * __builtin_amdgcn_rcpf(1.f + __expf(-g2));
;               const float y3 = o[m][4 * b + 3] * rn * sg.w * g3 * __builtin_amdgcn_rcpf(1.f + __expf(-g3));
;               pk[bb][0] = pk2(y0, y1); pk[bb][1] = pk2(y2, y3);
;             }
;             const auto r0 = __builtin_amdgcn_permlane32_swap(pk[0][0], pk[1][0], false, false);
;             const auto r1 = __builtin_amdgcn_permlane32_swap(pk[0][1], pk[1][1], false, false);
;             u32x4 w; w[0] = r0[0]; w[1] = r1[0]; w[2] = r0[1]; w[3] = r1[1];
;             *(u32x4*)(a.og + oo2 + 32 * m + 16 * bp) = w;
;             __builtin_amdgcn_sched_barrier(0);
;           }
	v_mov_b32_e32 v24, v184
	v_mov_b32_e32 v25, v185
	v_mov_b32_e32 v26, v186
	v_mov_b32_e32 v27, v187
	v_mov_b32_e32 v28, v244
	v_mov_b32_e32 v29, v245
	v_mov_b32_e32 v30, v246
	v_mov_b32_e32 v31, v247
	v_mov_b32_e32 v40, v248
	v_mov_b32_e32 v41, v249
	v_mov_b32_e32 v42, v250
	v_mov_b32_e32 v43, v251
	v_pk_mul_f32 v[44:45], v[88:89], v[0:1] op_sel_hi:[1,0]
	v_pk_mul_f32 v[88:89], v[92:93], v[0:1] op_sel_hi:[1,0]
	v_pk_mul_f32 v[46:47], v[90:91], v[0:1] op_sel_hi:[1,0]
	v_pk_mul_f32 v[90:91], v[94:95], v[0:1] op_sel_hi:[1,0]
	s_nop 0
	v_mov_b32_e32 v23, v26
	v_mov_b32_e32 v92, v27
	s_nop 0
	v_permlane32_swap_b32_e32 v24, v23
	v_permlane32_swap_b32_e32 v25, v92
	s_nop 0
	v_pk_mul_f32 v[26:27], v[44:45], v[28:29]
	v_pk_mul_f32 v[28:29], v[46:47], v[30:31]
	s_nop 0
	v_pk_mul_f32 v[30:31], v[88:89], v[40:41]
	v_pk_mul_f32 v[40:41], v[90:91], v[42:43]
	v_lshlrev_b32_e32 v42, 16, v24
	v_and_b32_e32 v43, 0xffff0000, v24
	v_lshlrev_b32_e32 v24, 16, v25
	v_and_b32_e32 v25, 0xffff0000, v25
	v_lshlrev_b32_e32 v44, 16, v23
	v_and_b32_e32 v45, 0xffff0000, v23
	v_lshlrev_b32_e32 v46, 16, v92
	v_and_b32_e32 v47, 0xffff0000, v92
	v_mul_f32_e32 v23, 0xbfb8aa3b, v42
	v_pk_mul_f32 v[26:27], v[26:27], v[42:43]
	v_mul_f32_e32 v42, 0xbfb8aa3b, v43
	v_mul_f32_e32 v43, 0xbfb8aa3b, v24
	v_pk_mul_f32 v[28:29], v[28:29], v[24:25]
	v_mul_f32_e32 v88, 0xbfb8aa3b, v25
	v_mul_f32_e32 v89, 0xbfb8aa3b, v44
	v_pk_mul_f32 v[24:25], v[30:31], v[44:45]
	v_mul_f32_e32 v44, 0xbfb8aa3b, v45
	v_mul_f32_e32 v45, 0xbfb8aa3b, v46
	v_pk_mul_f32 v[30:31], v[40:41], v[46:47]
	v_mul_f32_e32 v40, 0xbfb8aa3b, v47
	v_exp_f32_e32 v23, v23
	v_exp_f32_e32 v41, v42
	v_exp_f32_e32 v42, v43
	v_exp_f32_e32 v43, v88
	v_exp_f32_e32 v46, v89
	v_exp_f32_e32 v44, v44
	v_exp_f32_e32 v45, v45
	v_exp_f32_e32 v40, v40
	v_add_f32_e32 v23, 1.0, v23
	v_add_f32_e32 v41, 1.0, v41
	v_add_f32_e32 v42, 1.0, v42
	v_add_f32_e32 v43, 1.0, v43
	v_add_f32_e32 v46, 1.0, v46
	v_add_f32_e32 v47, 1.0, v44
	v_add_f32_e32 v88, 1.0, v45
	v_add_f32_e32 v89, 1.0, v40
	v_rcp_f32_e32 v40, v23
	v_rcp_f32_e32 v41, v41
	v_rcp_f32_e32 v42, v42
	v_rcp_f32_e32 v43, v43
	v_rcp_f32_e32 v44, v46
	v_rcp_f32_e32 v45, v47
	v_rcp_f32_e32 v46, v88
	v_rcp_f32_e32 v47, v89
	v_pk_mul_f32 v[26:27], v[26:27], v[40:41]
	v_pk_mul_f32 v[28:29], v[28:29], v[42:43]
	v_pk_mul_f32 v[40:41], v[44:45], v[24:25]
	v_pk_mul_f32 v[30:31], v[46:47], v[30:31]
	v_cvt_pk_bf16_f32 v24, v26, v27
	v_cvt_pk_bf16_f32 v25, v28, v29
	v_cvt_pk_bf16_f32 v26, v40, v41
	v_cvt_pk_bf16_f32 v27, v30, v31
	s_nop 0
	v_permlane32_swap_b32_e32 v24, v26
	v_permlane32_swap_b32_e32 v25, v27
	global_store_dwordx4 v[14:15], v[24:27], off offset:224
	s_nop 0
	global_load_dwordx4 v[244:247], v22, s[46:47] offset:576
	global_load_dwordx4 v[248:251], v22, s[46:47] offset:608
	s_waitcnt vmcnt(3)
	v_mov_b32_e32 v24, v188
	v_mov_b32_e32 v25, v189
	v_mov_b32_e32 v26, v190
	v_mov_b32_e32 v27, v191
	v_mov_b32_e32 v28, v156
	v_mov_b32_e32 v29, v157
	v_mov_b32_e32 v30, v158
	v_mov_b32_e32 v31, v159
	v_mov_b32_e32 v40, v240
	v_mov_b32_e32 v41, v241
	v_mov_b32_e32 v42, v242
	v_mov_b32_e32 v43, v243
	v_pk_mul_f32 v[46:47], v[84:85], v[0:1] op_sel_hi:[1,0]
	v_pk_mul_f32 v[44:45], v[86:87], v[0:1] op_sel_hi:[1,0]
	v_pk_mul_f32 v[82:83], v[82:83], v[0:1] op_sel_hi:[1,0]
	v_pk_mul_f32 v[80:81], v[80:81], v[0:1] op_sel_hi:[1,0]
	s_nop 0
	v_mov_b32_e32 v23, v26
	v_mov_b32_e32 v84, v27
	s_nop 0
	v_permlane32_swap_b32_e32 v24, v23
	v_permlane32_swap_b32_e32 v25, v84
	s_nop 0
	v_pk_mul_f32 v[26:27], v[44:45], v[28:29]
	v_pk_mul_f32 v[28:29], v[46:47], v[30:31]
	s_nop 0
	v_pk_mul_f32 v[30:31], v[82:83], v[40:41]
	v_pk_mul_f32 v[40:41], v[80:81], v[42:43]
	v_lshlrev_b32_e32 v42, 16, v24
	v_and_b32_e32 v43, 0xffff0000, v24
	v_lshlrev_b32_e32 v24, 16, v25
	v_and_b32_e32 v25, 0xffff0000, v25
	v_lshlrev_b32_e32 v44, 16, v23
	v_and_b32_e32 v45, 0xffff0000, v23
	v_lshlrev_b32_e32 v46, 16, v84
	v_and_b32_e32 v47, 0xffff0000, v84
	v_mul_f32_e32 v23, 0xbfb8aa3b, v42
	v_pk_mul_f32 v[26:27], v[26:27], v[42:43]
	v_mul_f32_e32 v42, 0xbfb8aa3b, v43
	v_mul_f32_e32 v43, 0xbfb8aa3b, v24
	v_pk_mul_f32 v[28:29], v[28:29], v[24:25]
	v_mul_f32_e32 v80, 0xbfb8aa3b, v25
	v_mul_f32_e32 v81, 0xbfb8aa3b, v44
	v_pk_mul_f32 v[24:25], v[30:31], v[44:45]
	v_mul_f32_e32 v44, 0xbfb8aa3b, v45
	v_mul_f32_e32 v45, 0xbfb8aa3b, v46
	v_pk_mul_f32 v[30:31], v[40:41], v[46:47]
	v_mul_f32_e32 v40, 0xbfb8aa3b, v47
	v_exp_f32_e32 v23, v23
	v_exp_f32_e32 v41, v42
	v_exp_f32_e32 v42, v43
	v_exp_f32_e32 v43, v80
	v_exp_f32_e32 v46, v81
	v_exp_f32_e32 v44, v44
	v_exp_f32_e32 v45, v45
	v_exp_f32_e32 v40, v40
	v_add_f32_e32 v23, 1.0, v23
	v_add_f32_e32 v41, 1.0, v41
	v_add_f32_e32 v42, 1.0, v42
	v_add_f32_e32 v43, 1.0, v43
	v_add_f32_e32 v46, 1.0, v46
	v_add_f32_e32 v47, 1.0, v44
	v_add_f32_e32 v80, 1.0, v45
	v_add_f32_e32 v81, 1.0, v40
	v_rcp_f32_e32 v40, v23
	v_rcp_f32_e32 v41, v41
	v_rcp_f32_e32 v42, v42
	v_rcp_f32_e32 v43, v43
	v_rcp_f32_e32 v44, v46
	v_rcp_f32_e32 v45, v47
	v_rcp_f32_e32 v46, v80
	v_rcp_f32_e32 v47, v81
	v_pk_mul_f32 v[26:27], v[26:27], v[40:41]
	v_pk_mul_f32 v[28:29], v[28:29], v[42:43]
	v_pk_mul_f32 v[40:41], v[44:45], v[24:25]
	v_pk_mul_f32 v[30:31], v[46:47], v[30:31]
	v_cvt_pk_bf16_f32 v24, v26, v27
	v_cvt_pk_bf16_f32 v25, v28, v29
	v_cvt_pk_bf16_f32 v26, v40, v41
	v_cvt_pk_bf16_f32 v27, v30, v31
	s_nop 0
	v_permlane32_swap_b32_e32 v24, v26
	v_permlane32_swap_b32_e32 v25, v27
	global_store_dwordx4 v[14:15], v[24:27], off offset:256
	s_nop 0
	global_load_dwordx4 v[156:159], v22, s[46:47] offset:640
	global_load_dwordx4 v[240:243], v22, s[46:47] offset:672
	s_waitcnt vmcnt(3)
; DI u32 pk2(float a, float b) { f2_t v = {a, b}; bf2_t r = __builtin_convertvector(v, bf2_t); return __builtin_bit_cast(u32, r); }
; DI float bflo(u32 u) { return __uint_as_float(u << 16); }
; DI float bfhi(u32 u) { return __uint_as_float(u & 0xffff0000u); }
; template <bool DIFF>
; DI void attn_phase(const AttnArgs& a, char* lds) {
;     ...
;         for (int m = 0; m < NM; ++m)
; #pragma unroll
;           for (int bp = 0; bp < 2; ++bp) {
;             u32x2 pk[2];
;             const u32x4 gl = *(const u32x4*)(a.gate + go2 + 32 * m + 16 * bp);
;             const auto q0 = __builtin_amdgcn_permlane32_swap(gl[0], gl[2], false, false);
;             const auto q1 = __builtin_amdgcn_permlane32_swap(gl[1], gl[3], false, false);
;             u32x2 gsel[2]; gsel[0][0] = q0[0]; gsel[0][1] = q1[0]; gsel[1][0] = q0[1]; gsel[1][1] = q1[1];
; #pragma unroll
;             for (int bb = 0; bb < 2; ++bb) {
;               const int b = 2 * bp + bb;
;               const int dv = 32 * m + 8 * b;
;               const u32x2 gu = gsel[bb];
;               const float4 sg = *(const float4*)(a.subln + dv + 4 * g);
;               const float g0 = bflo(gu[0]), g1 = bfhi(gu[0]), g2 = bflo(gu[1]), g3 = bfhi(gu[1]);
;               const float y0 = o[m][4 * b] * rn * sg.x * g0 * __builtin_amdgcn_rcpf(1.f + __expf(-g0));
;               const float y1 = o[m][4 * b + 1] * rn * sg.y * g1 * __builtin_amdgcn_rcpf(1.f + __expf(-g1));
;               const float y2 = o[m][4 * b + 2] * rn * sg.z * g2 * __builtin_amdgcn_rcpf(1.f + __expf(-g2));
;               const float y3 = o[m][4 * b + 3] * rn * sg.w * g3 * __builtin_amdgcn_rcpf(1.f + __expf(-g3));
;               pk[bb][0] = pk2(y0, y1); pk[bb][1] = pk2(y2, y3);
;             }
;             const auto r0 = __builtin_amdgcn_permlane32_swap(pk[0][0], pk[1][0], false, false);
;             const auto r1 = __builtin_amdgcn_permlane32_swap(pk[0][1], pk[1][1], false, false);
;             u32x4 w; w[0] = r0[0]; w[1] = r1[0]; w[2] = r0[1]; w[3] = r1[1];
;             *(u32x4*)(a.og + oo2 + 32 * m + 16 * bp) = w;
;             __builtin_amdgcn_sched_barrier(0);
;           }
	v_mov_b32_e32 v24, v192
	v_mov_b32_e32 v25, v193
	v_mov_b32_e32 v26, v194
	v_mov_b32_e32 v27, v195
	v_mov_b32_e32 v28, v244
	v_mov_b32_e32 v29, v245
	v_mov_b32_e32 v30, v246
	v_mov_b32_e32 v31, v247
	v_mov_b32_e32 v40, v248
	v_mov_b32_e32 v41, v249
	v_mov_b32_e32 v42, v250
	v_mov_b32_e32 v43, v251
	v_pk_mul_f32 v[44:45], v[72:73], v[0:1] op_sel_hi:[1,0]
	v_pk_mul_f32 v[72:73], v[76:77], v[0:1] op_sel_hi:[1,0]
	v_pk_mul_f32 v[46:47], v[74:75], v[0:1] op_sel_hi:[1,0]
	v_pk_mul_f32 v[74:75], v[78:79], v[0:1] op_sel_hi:[1,0]
	s_nop 0
	v_mov_b32_e32 v23, v26
	v_mov_b32_e32 v76, v27
	s_nop 0
	v_permlane32_swap_b32_e32 v24, v23
	v_permlane32_swap_b32_e32 v25, v76
	s_nop 0
	v_pk_mul_f32 v[26:27], v[44:45], v[28:29]
	v_pk_mul_f32 v[28:29], v[46:47], v[30:31]
	s_nop 0
	v_pk_mul_f32 v[30:31], v[72:73], v[40:41]
	v_pk_mul_f32 v[40:41], v[74:75], v[42:43]
	v_lshlrev_b32_e32 v42, 16, v24
	v_and_b32_e32 v43, 0xffff0000, v24
	v_lshlrev_b32_e32 v24, 16, v25
	v_and_b32_e32 v25, 0xffff0000, v25
	v_lshlrev_b32_e32 v44, 16, v23
	v_and_b32_e32 v45, 0xffff0000, v23
	v_lshlrev_b32_e32 v46, 16, v76
	v_and_b32_e32 v47, 0xffff0000, v76
	v_mul_f32_e32 v23, 0xbfb8aa3b, v42
	v_pk_mul_f32 v[26:27], v[26:27], v[42:43]
	v_mul_f32_e32 v42, 0xbfb8aa3b, v43
	v_mul_f32_e32 v43, 0xbfb8aa3b, v24
	v_pk_mul_f32 v[28:29], v[28:29], v[24:25]
	v_mul_f32_e32 v72, 0xbfb8aa3b, v25
	v_mul_f32_e32 v73, 0xbfb8aa3b, v44
	v_pk_mul_f32 v[24:25], v[30:31], v[44:45]
	v_mul_f32_e32 v44, 0xbfb8aa3b, v45
	v_mul_f32_e32 v45, 0xbfb8aa3b, v46
	v_pk_mul_f32 v[30:31], v[40:41], v[46:47]
	v_mul_f32_e32 v40, 0xbfb8aa3b, v47
	v_exp_f32_e32 v23, v23
	v_exp_f32_e32 v41, v42
	v_exp_f32_e32 v42, v43
	v_exp_f32_e32 v43, v72
	v_exp_f32_e32 v46, v73
	v_exp_f32_e32 v44, v44
	v_exp_f32_e32 v45, v45
	v_exp_f32_e32 v40, v40
	v_add_f32_e32 v23, 1.0, v23
	v_add_f32_e32 v41, 1.0, v41
	v_add_f32_e32 v42, 1.0, v42
	v_add_f32_e32 v43, 1.0, v43
	v_add_f32_e32 v46, 1.0, v46
	v_add_f32_e32 v47, 1.0, v44
	v_add_f32_e32 v72, 1.0, v45
	v_add_f32_e32 v73, 1.0, v40
	v_rcp_f32_e32 v40, v23
	v_rcp_f32_e32 v41, v41
	v_rcp_f32_e32 v42, v42
	v_rcp_f32_e32 v43, v43
	v_rcp_f32_e32 v44, v46
	v_rcp_f32_e32 v45, v47
	v_rcp_f32_e32 v46, v72
	v_rcp_f32_e32 v47, v73
	v_pk_mul_f32 v[26:27], v[26:27], v[40:41]
	v_pk_mul_f32 v[28:29], v[28:29], v[42:43]
	v_pk_mul_f32 v[40:41], v[44:45], v[24:25]
	v_pk_mul_f32 v[30:31], v[46:47], v[30:31]
	v_cvt_pk_bf16_f32 v24, v26, v27
	v_cvt_pk_bf16_f32 v25, v28, v29
	v_cvt_pk_bf16_f32 v26, v40, v41
	v_cvt_pk_bf16_f32 v27, v30, v31
	s_nop 0
	v_permlane32_swap_b32_e32 v24, v26
	v_permlane32_swap_b32_e32 v25, v27
	global_store_dwordx4 v[14:15], v[24:27], off offset:288
	s_nop 0
	global_load_dwordx4 v[244:247], v22, s[46:47] offset:704
	global_load_dwordx4 v[248:251], v22, s[46:47] offset:736
	s_waitcnt vmcnt(3)
	v_mov_b32_e32 v24, v196
	v_mov_b32_e32 v25, v197
	v_mov_b32_e32 v26, v198
	v_mov_b32_e32 v27, v199
	v_mov_b32_e32 v28, v156
	v_mov_b32_e32 v29, v157
	v_mov_b32_e32 v30, v158
	v_mov_b32_e32 v31, v159
	v_mov_b32_e32 v40, v240
	v_mov_b32_e32 v41, v241
	v_mov_b32_e32 v42, v242
	v_mov_b32_e32 v43, v243
	v_pk_mul_f32 v[46:47], v[68:69], v[0:1] op_sel_hi:[1,0]
	v_pk_mul_f32 v[44:45], v[70:71], v[0:1] op_sel_hi:[1,0]
	v_pk_mul_f32 v[66:67], v[66:67], v[0:1] op_sel_hi:[1,0]
	v_pk_mul_f32 v[64:65], v[64:65], v[0:1] op_sel_hi:[1,0]
	s_nop 0
	v_mov_b32_e32 v23, v26
	v_mov_b32_e32 v68, v27
	s_nop 0
	v_permlane32_swap_b32_e32 v24, v23
	v_permlane32_swap_b32_e32 v25, v68
	s_nop 0
	v_pk_mul_f32 v[26:27], v[44:45], v[28:29]
	v_pk_mul_f32 v[28:29], v[46:47], v[30:31]
	s_nop 0
	v_pk_mul_f32 v[30:31], v[66:67], v[40:41]
	v_pk_mul_f32 v[40:41], v[64:65], v[42:43]
	v_lshlrev_b32_e32 v42, 16, v24
	v_and_b32_e32 v43, 0xffff0000, v24
	v_lshlrev_b32_e32 v24, 16, v25
	v_and_b32_e32 v25, 0xffff0000, v25
	v_lshlrev_b32_e32 v44, 16, v23
	v_and_b32_e32 v45, 0xffff0000, v23
	v_lshlrev_b32_e32 v46, 16, v68
	v_and_b32_e32 v47, 0xffff0000, v68
	v_mul_f32_e32 v23, 0xbfb8aa3b, v42
	v_pk_mul_f32 v[26:27], v[26:27], v[42:43]
	v_mul_f32_e32 v42, 0xbfb8aa3b, v43
	v_mul_f32_e32 v43, 0xbfb8aa3b, v24
	v_pk_mul_f32 v[28:29], v[28:29], v[24:25]
	v_mul_f32_e32 v64, 0xbfb8aa3b, v25
	v_mul_f32_e32 v65, 0xbfb8aa3b, v44
	v_pk_mul_f32 v[24:25], v[30:31], v[44:45]
	v_mul_f32_e32 v44, 0xbfb8aa3b, v45
	v_mul_f32_e32 v45, 0xbfb8aa3b, v46
	v_pk_mul_f32 v[30:31], v[40:41], v[46:47]
	v_mul_f32_e32 v40, 0xbfb8aa3b, v47
	v_exp_f32_e32 v23, v23
	v_exp_f32_e32 v41, v42
	v_exp_f32_e32 v42, v43
	v_exp_f32_e32 v43, v64
	v_exp_f32_e32 v46, v65
	v_exp_f32_e32 v44, v44
	v_exp_f32_e32 v45, v45
	v_exp_f32_e32 v40, v40
	v_add_f32_e32 v23, 1.0, v23
	v_add_f32_e32 v41, 1.0, v41
	v_add_f32_e32 v42, 1.0, v42
	v_add_f32_e32 v43, 1.0, v43
	v_add_f32_e32 v46, 1.0, v46
	v_add_f32_e32 v47, 1.0, v44
	v_add_f32_e32 v64, 1.0, v45
	v_add_f32_e32 v65, 1.0, v40
	v_rcp_f32_e32 v40, v23
	v_rcp_f32_e32 v41, v41
	v_rcp_f32_e32 v42, v42
	v_rcp_f32_e32 v43, v43
	v_rcp_f32_e32 v44, v46
	v_rcp_f32_e32 v45, v47
	v_rcp_f32_e32 v46, v64
	v_rcp_f32_e32 v47, v65
	v_pk_mul_f32 v[26:27], v[26:27], v[40:41]
	v_pk_mul_f32 v[28:29], v[28:29], v[42:43]
	v_pk_mul_f32 v[40:41], v[44:45], v[24:25]
	v_pk_mul_f32 v[30:31], v[46:47], v[30:31]
	v_cvt_pk_bf16_f32 v24, v26, v27
	v_cvt_pk_bf16_f32 v25, v28, v29
	v_cvt_pk_bf16_f32 v26, v40, v41
	v_cvt_pk_bf16_f32 v27, v30, v31
	s_nop 0
	v_permlane32_swap_b32_e32 v24, v26
	v_permlane32_swap_b32_e32 v25, v27
	global_store_dwordx4 v[14:15], v[24:27], off offset:320
	s_nop 0
	global_load_dwordx4 v[156:159], v22, s[46:47] offset:768
	global_load_dwordx4 v[240:243], v22, s[46:47] offset:800
	s_waitcnt vmcnt(3)
; DI u32 pk2(float a, float b) { f2_t v = {a, b}; bf2_t r = __builtin_convertvector(v, bf2_t); return __builtin_bit_cast(u32, r); }
; DI float bflo(u32 u) { return __uint_as_float(u << 16); }
; DI float bfhi(u32 u) { return __uint_as_float(u & 0xffff0000u); }
; template <bool DIFF>
; DI void attn_phase(const AttnArgs& a, char* lds) {
;     ...
;         for (int m = 0; m < NM; ++m)
; #pragma unroll
;           for (int bp = 0; bp < 2; ++bp) {
;             u32x2 pk[2];
;             const u32x4 gl = *(const u32x4*)(a.gate + go2 + 32 * m + 16 * bp);
;             const auto q0 = __builtin_amdgcn_permlane32_swap(gl[0], gl[2], false, false);
;             const auto q1 = __builtin_amdgcn_permlane32_swap(gl[1], gl[3], false, false);
;             u32x2 gsel[2]; gsel[0][0] = q0[0]; gsel[0][1] = q1[0]; gsel[1][0] = q0[1]; gsel[1][1] = q1[1];
; #pragma unroll
;             for (int bb = 0; bb < 2; ++bb) {
;               const int b = 2 * bp + bb;
;               const int dv = 32 * m + 8 * b;
;               const u32x2 gu = gsel[bb];
;               const float4 sg = *(const float4*)(a.subln + dv + 4 * g);
;               const float g0 = bflo(gu[0]), g1 = bfhi(gu[0]), g2 = bflo(gu[1]), g3 = bfhi(gu[1]);
;               const float y0 = o[m][4 * b] * rn * sg.x * g0 * __builtin_amdgcn_rcpf(1.f + __expf(-g0));
;               const float y1 = o[m][4 * b + 1] * rn * sg.y * g1 * __builtin_amdgcn_rcpf(1.f + __expf(-g1));
;               const float y2 = o[m][4 * b + 2] * rn * sg.z * g2 * __builtin_amdgcn_rcpf(1.f + __expf(-g2));
;               const float y3 = o[m][4 * b + 3] * rn * sg.w * g3 * __builtin_amdgcn_rcpf(1.f + __expf(-g3));
;               pk[bb][0] = pk2(y0, y1); pk[bb][1] = pk2(y2, y3);
;             }
;             const auto r0 = __builtin_amdgcn_permlane32_swap(pk[0][0], pk[1][0], false, false);
;             const auto r1 = __builtin_amdgcn_permlane32_swap(pk[0][1], pk[1][1], false, false);
;             u32x4 w; w[0] = r0[0]; w[1] = r1[0]; w[2] = r0[1]; w[3] = r1[1];
;             *(u32x4*)(a.og + oo2 + 32 * m + 16 * bp) = w;
;             __builtin_amdgcn_sched_barrier(0);
;           }
	v_mov_b32_e32 v24, v200
	v_mov_b32_e32 v25, v201
	v_mov_b32_e32 v26, v202
	v_mov_b32_e32 v27, v203
	v_mov_b32_e32 v28, v244
	v_mov_b32_e32 v29, v245
	v_mov_b32_e32 v30, v246
	v_mov_b32_e32 v31, v247
	v_mov_b32_e32 v40, v248
	v_mov_b32_e32 v41, v249
	v_mov_b32_e32 v42, v250
	v_mov_b32_e32 v43, v251
	v_pk_mul_f32 v[44:45], v[56:57], v[0:1] op_sel_hi:[1,0]
	v_pk_mul_f32 v[56:57], v[60:61], v[0:1] op_sel_hi:[1,0]
	v_pk_mul_f32 v[46:47], v[58:59], v[0:1] op_sel_hi:[1,0]
	v_pk_mul_f32 v[58:59], v[62:63], v[0:1] op_sel_hi:[1,0]
	s_nop 0
	v_mov_b32_e32 v23, v26
	v_mov_b32_e32 v60, v27
	s_nop 0
	v_permlane32_swap_b32_e32 v24, v23
	v_permlane32_swap_b32_e32 v25, v60
	s_nop 0
	v_pk_mul_f32 v[26:27], v[44:45], v[28:29]
	v_pk_mul_f32 v[28:29], v[46:47], v[30:31]
	s_nop 0
	v_pk_mul_f32 v[30:31], v[56:57], v[40:41]
	v_pk_mul_f32 v[40:41], v[58:59], v[42:43]
	v_lshlrev_b32_e32 v42, 16, v24
	v_and_b32_e32 v43, 0xffff0000, v24
	v_lshlrev_b32_e32 v24, 16, v25
	v_and_b32_e32 v25, 0xffff0000, v25
	v_lshlrev_b32_e32 v44, 16, v23
	v_and_b32_e32 v45, 0xffff0000, v23
	v_lshlrev_b32_e32 v46, 16, v60
	v_and_b32_e32 v47, 0xffff0000, v60
	v_mul_f32_e32 v23, 0xbfb8aa3b, v42
	v_pk_mul_f32 v[26:27], v[26:27], v[42:43]
	v_mul_f32_e32 v42, 0xbfb8aa3b, v43
	v_mul_f32_e32 v43, 0xbfb8aa3b, v24
	v_pk_mul_f32 v[28:29], v[28:29], v[24:25]
	v_mul_f32_e32 v56, 0xbfb8aa3b, v25
	v_mul_f32_e32 v57, 0xbfb8aa3b, v44
	v_pk_mul_f32 v[24:25], v[30:31], v[44:45]
	v_mul_f32_e32 v44, 0xbfb8aa3b, v45
	v_mul_f32_e32 v45, 0xbfb8aa3b, v46
	v_pk_mul_f32 v[30:31], v[40:41], v[46:47]
	v_mul_f32_e32 v40, 0xbfb8aa3b, v47
	v_exp_f32_e32 v23, v23
	v_exp_f32_e32 v41, v42
	v_exp_f32_e32 v42, v43
	v_exp_f32_e32 v43, v56
	v_exp_f32_e32 v46, v57
	v_exp_f32_e32 v44, v44
	v_exp_f32_e32 v45, v45
	v_exp_f32_e32 v40, v40
	v_add_f32_e32 v23, 1.0, v23
	v_add_f32_e32 v41, 1.0, v41
	v_add_f32_e32 v42, 1.0, v42
	v_add_f32_e32 v43, 1.0, v43
	v_add_f32_e32 v46, 1.0, v46
	v_add_f32_e32 v47, 1.0, v44
	v_add_f32_e32 v56, 1.0, v45
	v_add_f32_e32 v57, 1.0, v40
	v_rcp_f32_e32 v40, v23
	v_rcp_f32_e32 v41, v41
	v_rcp_f32_e32 v42, v42
	v_rcp_f32_e32 v43, v43
	v_rcp_f32_e32 v44, v46
	v_rcp_f32_e32 v45, v47
	v_rcp_f32_e32 v46, v56
	v_rcp_f32_e32 v47, v57
	v_pk_mul_f32 v[26:27], v[26:27], v[40:41]
	v_pk_mul_f32 v[28:29], v[28:29], v[42:43]
	v_pk_mul_f32 v[40:41], v[44:45], v[24:25]
	v_pk_mul_f32 v[30:31], v[46:47], v[30:31]
	v_cvt_pk_bf16_f32 v24, v26, v27
	v_cvt_pk_bf16_f32 v25, v28, v29
	v_cvt_pk_bf16_f32 v26, v40, v41
	v_cvt_pk_bf16_f32 v27, v30, v31
	s_nop 0
	v_permlane32_swap_b32_e32 v24, v26
	v_permlane32_swap_b32_e32 v25, v27
	global_store_dwordx4 v[14:15], v[24:27], off offset:352
	s_nop 0
	global_load_dwordx4 v[244:247], v22, s[46:47] offset:832
	global_load_dwordx4 v[248:251], v22, s[46:47] offset:864
	s_waitcnt vmcnt(3)
	v_mov_b32_e32 v24, v204
	v_mov_b32_e32 v25, v205
	v_mov_b32_e32 v26, v206
	v_mov_b32_e32 v27, v207
	v_mov_b32_e32 v28, v156
	v_mov_b32_e32 v29, v157
	v_mov_b32_e32 v30, v158
	v_mov_b32_e32 v31, v159
	v_mov_b32_e32 v40, v240
	v_mov_b32_e32 v41, v241
	v_mov_b32_e32 v42, v242
	v_mov_b32_e32 v43, v243
	v_pk_mul_f32 v[46:47], v[52:53], v[0:1] op_sel_hi:[1,0]
	v_pk_mul_f32 v[44:45], v[54:55], v[0:1] op_sel_hi:[1,0]
	v_pk_mul_f32 v[50:51], v[50:51], v[0:1] op_sel_hi:[1,0]
	v_pk_mul_f32 v[48:49], v[48:49], v[0:1] op_sel_hi:[1,0]
	s_nop 0
	v_mov_b32_e32 v23, v26
	v_mov_b32_e32 v52, v27
	s_nop 0
	v_permlane32_swap_b32_e32 v24, v23
	v_permlane32_swap_b32_e32 v25, v52
	s_nop 0
	v_pk_mul_f32 v[26:27], v[44:45], v[28:29]
	v_pk_mul_f32 v[28:29], v[46:47], v[30:31]
	s_nop 0
	v_pk_mul_f32 v[30:31], v[50:51], v[40:41]
	v_pk_mul_f32 v[40:41], v[48:49], v[42:43]
	v_lshlrev_b32_e32 v42, 16, v24
	v_and_b32_e32 v43, 0xffff0000, v24
	v_lshlrev_b32_e32 v24, 16, v25
	v_and_b32_e32 v25, 0xffff0000, v25
	v_lshlrev_b32_e32 v44, 16, v23
	v_and_b32_e32 v45, 0xffff0000, v23
	v_lshlrev_b32_e32 v46, 16, v52
	v_and_b32_e32 v47, 0xffff0000, v52
	v_mul_f32_e32 v23, 0xbfb8aa3b, v42
	v_pk_mul_f32 v[26:27], v[26:27], v[42:43]
	v_mul_f32_e32 v42, 0xbfb8aa3b, v43
	v_mul_f32_e32 v43, 0xbfb8aa3b, v24
	v_pk_mul_f32 v[28:29], v[28:29], v[24:25]
	v_mul_f32_e32 v48, 0xbfb8aa3b, v25
	v_mul_f32_e32 v49, 0xbfb8aa3b, v44
	v_pk_mul_f32 v[24:25], v[30:31], v[44:45]
	v_mul_f32_e32 v44, 0xbfb8aa3b, v45
	v_mul_f32_e32 v45, 0xbfb8aa3b, v46
	v_pk_mul_f32 v[30:31], v[40:41], v[46:47]
	v_mul_f32_e32 v40, 0xbfb8aa3b, v47
	v_exp_f32_e32 v23, v23
	v_exp_f32_e32 v41, v42
	v_exp_f32_e32 v42, v43
	v_exp_f32_e32 v43, v48
	v_exp_f32_e32 v46, v49
	v_exp_f32_e32 v44, v44
	v_exp_f32_e32 v45, v45
	v_exp_f32_e32 v40, v40
	v_add_f32_e32 v23, 1.0, v23
	v_add_f32_e32 v41, 1.0, v41
	v_add_f32_e32 v42, 1.0, v42
	v_add_f32_e32 v43, 1.0, v43
	v_add_f32_e32 v46, 1.0, v46
	v_add_f32_e32 v47, 1.0, v44
	v_add_f32_e32 v48, 1.0, v45
	v_add_f32_e32 v49, 1.0, v40
	v_rcp_f32_e32 v40, v23
	v_rcp_f32_e32 v41, v41
	v_rcp_f32_e32 v42, v42
	v_rcp_f32_e32 v43, v43
	v_rcp_f32_e32 v44, v46
	v_rcp_f32_e32 v45, v47
	v_rcp_f32_e32 v46, v48
	v_rcp_f32_e32 v47, v49
	v_pk_mul_f32 v[26:27], v[26:27], v[40:41]
	v_pk_mul_f32 v[28:29], v[28:29], v[42:43]
	v_pk_mul_f32 v[40:41], v[44:45], v[24:25]
	v_pk_mul_f32 v[30:31], v[46:47], v[30:31]
	v_cvt_pk_bf16_f32 v24, v26, v27
	v_cvt_pk_bf16_f32 v25, v28, v29
	v_cvt_pk_bf16_f32 v26, v40, v41
	v_cvt_pk_bf16_f32 v27, v30, v31
	s_nop 0
	v_permlane32_swap_b32_e32 v24, v26
	v_permlane32_swap_b32_e32 v25, v27
	global_store_dwordx4 v[14:15], v[24:27], off offset:384
	s_nop 0
	global_load_dwordx4 v[156:159], v22, s[46:47] offset:896
	global_load_dwordx4 v[240:243], v22, s[46:47] offset:928
	s_waitcnt vmcnt(3)
; DI u32 pk2(float a, float b) { f2_t v = {a, b}; bf2_t r = __builtin_convertvector(v, bf2_t); return __builtin_bit_cast(u32, r); }
; DI float bflo(u32 u) { return __uint_as_float(u << 16); }
; DI float bfhi(u32 u) { return __uint_as_float(u & 0xffff0000u); }
; template <bool DIFF>
; DI void attn_phase(const AttnArgs& a, char* lds) {
;     ...
;         for (int m = 0; m < NM; ++m)
; #pragma unroll
;           for (int bp = 0; bp < 2; ++bp) {
;             u32x2 pk[2];
;             const u32x4 gl = *(const u32x4*)(a.gate + go2 + 32 * m + 16 * bp);
;             const auto q0 = __builtin_amdgcn_permlane32_swap(gl[0], gl[2], false, false);
;             const auto q1 = __builtin_amdgcn_permlane32_swap(gl[1], gl[3], false, false);
;             u32x2 gsel[2]; gsel[0][0] = q0[0]; gsel[0][1] = q1[0]; gsel[1][0] = q0[1]; gsel[1][1] = q1[1];
; #pragma unroll
;             for (int bb = 0; bb < 2; ++bb) {
;               const int b = 2 * bp + bb;
;               const int dv = 32 * m + 8 * b;
;               const u32x2 gu = gsel[bb];
;               const float4 sg = *(const float4*)(a.subln + dv + 4 * g);
;               const float g0 = bflo(gu[0]), g1 = bfhi(gu[0]), g2 = bflo(gu[1]), g3 = bfhi(gu[1]);
;               const float y0 = o[m][4 * b] * rn * sg.x * g0 * __builtin_amdgcn_rcpf(1.f + __expf(-g0));
;               const float y1 = o[m][4 * b + 1] * rn * sg.y * g1 * __builtin_amdgcn_rcpf(1.f + __expf(-g1));
;               const float y2 = o[m][4 * b + 2] * rn * sg.z * g2 * __builtin_amdgcn_rcpf(1.f + __expf(-g2));
;               const float y3 = o[m][4 * b + 3] * rn * sg.w * g3 * __builtin_amdgcn_rcpf(1.f + __expf(-g3));
;               pk[bb][0] = pk2(y0, y1); pk[bb][1] = pk2(y2, y3);
;             }
;             const auto r0 = __builtin_amdgcn_permlane32_swap(pk[0][0], pk[1][0], false, false);
;             const auto r1 = __builtin_amdgcn_permlane32_swap(pk[0][1], pk[1][1], false, false);
;             u32x4 w; w[0] = r0[0]; w[1] = r1[0]; w[2] = r0[1]; w[3] = r1[1];
;             *(u32x4*)(a.og + oo2 + 32 * m + 16 * bp) = w;
;             __builtin_amdgcn_sched_barrier(0);
;           }
	v_mov_b32_e32 v24, v228
	v_mov_b32_e32 v25, v229
	v_mov_b32_e32 v26, v230
	v_mov_b32_e32 v27, v231
	v_mov_b32_e32 v28, v244
	v_mov_b32_e32 v29, v245
	v_mov_b32_e32 v30, v246
	v_mov_b32_e32 v31, v247
	v_mov_b32_e32 v40, v248
	v_mov_b32_e32 v41, v249
	v_mov_b32_e32 v42, v250
	v_mov_b32_e32 v43, v251
	v_pk_mul_f32 v[38:39], v[38:39], v[0:1] op_sel_hi:[1,0]
	v_pk_mul_f32 v[36:37], v[36:37], v[0:1] op_sel_hi:[1,0]
	v_pk_mul_f32 v[34:35], v[34:35], v[0:1] op_sel_hi:[1,0]
	v_pk_mul_f32 v[32:33], v[32:33], v[0:1] op_sel_hi:[1,0]
	s_nop 0
	v_mov_b32_e32 v23, v26
	v_mov_b32_e32 v44, v27
	s_nop 0
	v_permlane32_swap_b32_e32 v24, v23
	v_permlane32_swap_b32_e32 v25, v44
	s_nop 0
	v_pk_mul_f32 v[26:27], v[38:39], v[28:29]
	v_pk_mul_f32 v[28:29], v[36:37], v[30:31]
	s_nop 0
	v_pk_mul_f32 v[30:31], v[34:35], v[40:41]
	v_pk_mul_f32 v[32:33], v[32:33], v[42:43]
	v_lshlrev_b32_e32 v34, 16, v24
	v_and_b32_e32 v35, 0xffff0000, v24
	v_lshlrev_b32_e32 v24, 16, v25
	v_and_b32_e32 v25, 0xffff0000, v25
	v_lshlrev_b32_e32 v36, 16, v23
	v_and_b32_e32 v37, 0xffff0000, v23
	v_lshlrev_b32_e32 v38, 16, v44
	v_and_b32_e32 v39, 0xffff0000, v44
	v_mul_f32_e32 v23, 0xbfb8aa3b, v34
	v_pk_mul_f32 v[26:27], v[26:27], v[34:35]
	v_mul_f32_e32 v34, 0xbfb8aa3b, v35
	v_mul_f32_e32 v35, 0xbfb8aa3b, v24
	v_pk_mul_f32 v[28:29], v[28:29], v[24:25]
	v_mul_f32_e32 v40, 0xbfb8aa3b, v25
	v_mul_f32_e32 v41, 0xbfb8aa3b, v36
	v_pk_mul_f32 v[24:25], v[30:31], v[36:37]
	v_mul_f32_e32 v36, 0xbfb8aa3b, v37
	v_mul_f32_e32 v37, 0xbfb8aa3b, v38
	v_pk_mul_f32 v[30:31], v[32:33], v[38:39]
	v_mul_f32_e32 v32, 0xbfb8aa3b, v39
	v_exp_f32_e32 v23, v23
	v_exp_f32_e32 v33, v34
	v_exp_f32_e32 v34, v35
	v_exp_f32_e32 v35, v40
	v_exp_f32_e32 v38, v41
	v_exp_f32_e32 v36, v36
	v_exp_f32_e32 v37, v37
	v_exp_f32_e32 v32, v32
	v_add_f32_e32 v23, 1.0, v23
	v_add_f32_e32 v33, 1.0, v33
	v_add_f32_e32 v34, 1.0, v34
	v_add_f32_e32 v35, 1.0, v35
	v_add_f32_e32 v38, 1.0, v38
	v_add_f32_e32 v39, 1.0, v36
	v_add_f32_e32 v40, 1.0, v37
	v_add_f32_e32 v41, 1.0, v32
	v_rcp_f32_e32 v32, v23
	v_rcp_f32_e32 v33, v33
	v_rcp_f32_e32 v34, v34
	v_rcp_f32_e32 v35, v35
	v_rcp_f32_e32 v36, v38
	v_rcp_f32_e32 v37, v39
	v_rcp_f32_e32 v38, v40
	v_rcp_f32_e32 v39, v41
	v_pk_mul_f32 v[26:27], v[26:27], v[32:33]
	v_pk_mul_f32 v[28:29], v[28:29], v[34:35]
	v_pk_mul_f32 v[32:33], v[36:37], v[24:25]
	v_pk_mul_f32 v[30:31], v[38:39], v[30:31]
	v_cvt_pk_bf16_f32 v24, v26, v27
	v_cvt_pk_bf16_f32 v25, v28, v29
	v_cvt_pk_bf16_f32 v26, v32, v33
	v_cvt_pk_bf16_f32 v27, v30, v31
	s_nop 0
	v_permlane32_swap_b32_e32 v24, v26
	v_permlane32_swap_b32_e32 v25, v27
	global_store_dwordx4 v[14:15], v[24:27], off offset:416
	s_nop 0
	global_load_dwordx4 v[244:247], v22, s[46:47] offset:960
	global_load_dwordx4 v[248:251], v22, s[46:47] offset:992
	s_waitcnt vmcnt(3)
; DI u32 pk2(float a, float b) { f2_t v = {a, b}; bf2_t r = __builtin_convertvector(v, bf2_t); return __builtin_bit_cast(u32, r); }
; DI float bflo(u32 u) { return __uint_as_float(u << 16); }
; DI float bfhi(u32 u) { return __uint_as_float(u & 0xffff0000u); }
; template <bool DIFF>
; DI void attn_phase(const AttnArgs& a, char* lds) {
;     ...
;         for (int m = 0; m < NM; ++m)
; #pragma unroll
;           for (int bp = 0; bp < 2; ++bp) {
;             u32x2 pk[2];
;             const u32x4 gl = *(const u32x4*)(a.gate + go2 + 32 * m + 16 * bp);
;             const auto q0 = __builtin_amdgcn_permlane32_swap(gl[0], gl[2], false, false);
;             const auto q1 = __builtin_amdgcn_permlane32_swap(gl[1], gl[3], false, false);
;             u32x2 gsel[2]; gsel[0][0] = q0[0]; gsel[0][1] = q1[0]; gsel[1][0] = q0[1]; gsel[1][1] = q1[1];
; #pragma unroll
;             for (int bb = 0; bb < 2; ++bb) {
;               const int b = 2 * bp + bb;
;               const int dv = 32 * m + 8 * b;
;               const u32x2 gu = gsel[bb];
;               const float4 sg = *(const float4*)(a.subln + dv + 4 * g);
;               const float g0 = bflo(gu[0]), g1 = bfhi(gu[0]), g2 = bflo(gu[1]), g3 = bfhi(gu[1]);
;               const float y0 = o[m][4 * b] * rn * sg.x * g0 * __builtin_amdgcn_rcpf(1.f + __expf(-g0));
;               const float y1 = o[m][4 * b + 1] * rn * sg.y * g1 * __builtin_amdgcn_rcpf(1.f + __expf(-g1));
;               const float y2 = o[m][4 * b + 2] * rn * sg.z * g2 * __builtin_amdgcn_rcpf(1.f + __expf(-g2));
;               const float y3 = o[m][4 * b + 3] * rn * sg.w * g3 * __builtin_amdgcn_rcpf(1.f + __expf(-g3));
;               pk[bb][0] = pk2(y0, y1); pk[bb][1] = pk2(y2, y3);
;             }
;             const auto r0 = __builtin_amdgcn_permlane32_swap(pk[0][0], pk[1][0], false, false);
;             const auto r1 = __builtin_amdgcn_permlane32_swap(pk[0][1], pk[1][1], false, false);
;             u32x4 w; w[0] = r0[0]; w[1] = r1[0]; w[2] = r0[1]; w[3] = r1[1];
;             *(u32x4*)(a.og + oo2 + 32 * m + 16 * bp) = w;
;             __builtin_amdgcn_sched_barrier(0);
;           }
	v_mov_b32_e32 v24, v232
	v_mov_b32_e32 v25, v233
	v_mov_b32_e32 v26, v234
	v_mov_b32_e32 v27, v235
	v_mov_b32_e32 v28, v156
	v_mov_b32_e32 v29, v157
	v_mov_b32_e32 v30, v158
	v_mov_b32_e32 v31, v159
	v_mov_b32_e32 v32, v240
	v_mov_b32_e32 v33, v241
	v_mov_b32_e32 v34, v242
	v_mov_b32_e32 v35, v243
	v_pk_mul_f32 v[16:17], v[16:17], v[0:1] op_sel_hi:[1,0]
	v_pk_mul_f32 v[18:19], v[18:19], v[0:1] op_sel_hi:[1,0]
	v_pk_mul_f32 v[20:21], v[20:21], v[0:1] op_sel_hi:[1,0]
	v_pk_mul_f32 v[10:11], v[10:11], v[0:1] op_sel_hi:[1,0]
	s_nop 0
	v_mov_b32_e32 v23, v26
	v_mov_b32_e32 v36, v27
	s_nop 0
	v_permlane32_swap_b32_e32 v24, v23
	v_permlane32_swap_b32_e32 v25, v36
	s_nop 0
	v_pk_mul_f32 v[16:17], v[16:17], v[28:29]
	v_pk_mul_f32 v[18:19], v[18:19], v[30:31]
	s_nop 0
	v_pk_mul_f32 v[20:21], v[20:21], v[32:33]
	v_pk_mul_f32 v[10:11], v[10:11], v[34:35]
	v_lshlrev_b32_e32 v26, 16, v24
	v_and_b32_e32 v27, 0xffff0000, v24
	v_lshlrev_b32_e32 v24, 16, v25
	v_and_b32_e32 v25, 0xffff0000, v25
	v_lshlrev_b32_e32 v28, 16, v23
	v_and_b32_e32 v29, 0xffff0000, v23
	v_lshlrev_b32_e32 v30, 16, v36
	v_and_b32_e32 v31, 0xffff0000, v36
	v_mul_f32_e32 v23, 0xbfb8aa3b, v26
	v_pk_mul_f32 v[16:17], v[16:17], v[26:27]
	v_mul_f32_e32 v26, 0xbfb8aa3b, v27
	v_mul_f32_e32 v27, 0xbfb8aa3b, v24
	v_pk_mul_f32 v[18:19], v[18:19], v[24:25]
	v_mul_f32_e32 v24, 0xbfb8aa3b, v25
	v_mul_f32_e32 v25, 0xbfb8aa3b, v28
	v_pk_mul_f32 v[20:21], v[20:21], v[28:29]
	v_mul_f32_e32 v28, 0xbfb8aa3b, v29
	v_mul_f32_e32 v29, 0xbfb8aa3b, v30
	v_pk_mul_f32 v[10:11], v[10:11], v[30:31]
	v_mul_f32_e32 v30, 0xbfb8aa3b, v31
	v_exp_f32_e32 v23, v23
	v_exp_f32_e32 v26, v26
	v_exp_f32_e32 v27, v27
	v_exp_f32_e32 v24, v24
	v_exp_f32_e32 v25, v25
	v_exp_f32_e32 v28, v28
	v_exp_f32_e32 v29, v29
	v_exp_f32_e32 v30, v30
	v_add_f32_e32 v23, 1.0, v23
	v_add_f32_e32 v26, 1.0, v26
	v_add_f32_e32 v27, 1.0, v27
	v_add_f32_e32 v31, 1.0, v24
	v_add_f32_e32 v32, 1.0, v25
	v_add_f32_e32 v33, 1.0, v28
	v_add_f32_e32 v34, 1.0, v29
	v_add_f32_e32 v35, 1.0, v30
	v_rcp_f32_e32 v24, v23
	v_rcp_f32_e32 v25, v26
	v_rcp_f32_e32 v26, v27
	v_rcp_f32_e32 v27, v31
	v_rcp_f32_e32 v28, v32
	v_rcp_f32_e32 v29, v33
	v_rcp_f32_e32 v30, v34
	v_rcp_f32_e32 v31, v35
	v_pk_mul_f32 v[16:17], v[16:17], v[24:25]
	v_pk_mul_f32 v[18:19], v[18:19], v[26:27]
	v_pk_mul_f32 v[20:21], v[28:29], v[20:21]
	v_pk_mul_f32 v[10:11], v[30:31], v[10:11]
	v_cvt_pk_bf16_f32 v16, v16, v17
	v_cvt_pk_bf16_f32 v17, v18, v19
	v_cvt_pk_bf16_f32 v18, v20, v21
	v_cvt_pk_bf16_f32 v19, v10, v11
	s_nop 0
	v_permlane32_swap_b32_e32 v16, v18
	v_permlane32_swap_b32_e32 v17, v19
	global_store_dwordx4 v[14:15], v[16:19], off offset:448
	s_nop 0
	s_nop 0
	s_nop 0
	s_nop 0
	s_waitcnt vmcnt(1)
	v_mov_b32_e32 v10, v236
	v_mov_b32_e32 v11, v237
	v_mov_b32_e32 v12, v238
	v_mov_b32_e32 v13, v239
	v_mov_b32_e32 v16, v244
	v_mov_b32_e32 v17, v245
	v_mov_b32_e32 v18, v246
	v_mov_b32_e32 v19, v247
	v_mov_b32_e32 v20, v248
	v_mov_b32_e32 v21, v249
	v_mov_b32_e32 v22, v250
	v_mov_b32_e32 v23, v251
	v_pk_mul_f32 v[8:9], v[8:9], v[0:1] op_sel_hi:[1,0]
	v_pk_mul_f32 v[6:7], v[6:7], v[0:1] op_sel_hi:[1,0]
	v_pk_mul_f32 v[4:5], v[4:5], v[0:1] op_sel_hi:[1,0]
	v_pk_mul_f32 v[2:3], v[2:3], v[0:1] op_sel_hi:[1,0]
	s_nop 0
	v_mov_b32_e32 v0, v12
	v_mov_b32_e32 v24, v13
	s_nop 0
	v_permlane32_swap_b32_e32 v10, v0
	v_permlane32_swap_b32_e32 v11, v24
	s_nop 0
	v_pk_mul_f32 v[8:9], v[8:9], v[16:17]
	v_pk_mul_f32 v[6:7], v[6:7], v[18:19]
	s_nop 0
	v_pk_mul_f32 v[4:5], v[4:5], v[20:21]
	v_pk_mul_f32 v[2:3], v[2:3], v[22:23]
	v_lshlrev_b32_e32 v12, 16, v10
	v_and_b32_e32 v13, 0xffff0000, v10
	v_lshlrev_b32_e32 v10, 16, v11
	v_and_b32_e32 v11, 0xffff0000, v11
	v_lshlrev_b32_e32 v16, 16, v0
	v_and_b32_e32 v17, 0xffff0000, v0
	v_lshlrev_b32_e32 v18, 16, v24
	v_and_b32_e32 v19, 0xffff0000, v24
	v_mul_f32_e32 v0, 0xbfb8aa3b, v12
	v_pk_mul_f32 v[8:9], v[8:9], v[12:13]
	v_mul_f32_e32 v12, 0xbfb8aa3b, v13
	v_mul_f32_e32 v13, 0xbfb8aa3b, v10
	v_pk_mul_f32 v[6:7], v[6:7], v[10:11]
	v_mul_f32_e32 v10, 0xbfb8aa3b, v11
	v_mul_f32_e32 v11, 0xbfb8aa3b, v16
	v_pk_mul_f32 v[4:5], v[4:5], v[16:17]
	v_mul_f32_e32 v16, 0xbfb8aa3b, v17
	v_mul_f32_e32 v17, 0xbfb8aa3b, v18
	v_pk_mul_f32 v[2:3], v[2:3], v[18:19]
	v_mul_f32_e32 v18, 0xbfb8aa3b, v19
	v_exp_f32_e32 v0, v0
	v_exp_f32_e32 v12, v12
	v_exp_f32_e32 v13, v13
	v_exp_f32_e32 v10, v10
	v_exp_f32_e32 v11, v11
	v_exp_f32_e32 v16, v16
	v_exp_f32_e32 v17, v17
	v_exp_f32_e32 v18, v18
	v_add_f32_e32 v0, 1.0, v0
	v_add_f32_e32 v12, 1.0, v12
	v_add_f32_e32 v13, 1.0, v13
	v_add_f32_e32 v19, 1.0, v10
	v_add_f32_e32 v20, 1.0, v11
	v_add_f32_e32 v21, 1.0, v16
	v_add_f32_e32 v22, 1.0, v17
	v_add_f32_e32 v23, 1.0, v18
	v_rcp_f32_e32 v10, v0
	v_rcp_f32_e32 v11, v12
	v_rcp_f32_e32 v12, v13
	v_rcp_f32_e32 v13, v19
	v_rcp_f32_e32 v16, v20
	v_rcp_f32_e32 v17, v21
	v_rcp_f32_e32 v18, v22
	v_rcp_f32_e32 v19, v23
	v_pk_mul_f32 v[8:9], v[8:9], v[10:11]
	v_pk_mul_f32 v[6:7], v[6:7], v[12:13]
	v_pk_mul_f32 v[4:5], v[16:17], v[4:5]
	v_pk_mul_f32 v[10:11], v[18:19], v[2:3]
	v_cvt_pk_bf16_f32 v2, v8, v9
	v_cvt_pk_bf16_f32 v3, v6, v7
	v_cvt_pk_bf16_f32 v4, v4, v5
	v_cvt_pk_bf16_f32 v5, v10, v11
	s_nop 0
	v_permlane32_swap_b32_e32 v2, v4
	v_permlane32_swap_b32_e32 v3, v5
	global_store_dwordx4 v[14:15], v[2:5], off offset:480
	s_branch .LBB0_587
